# GEMM MFMA blocks: second 16-MFMA run reversed so the snake (shared operand between neighbours) continues across the whole 32-MFMA block; mid-block setprio pair dropped
# baseline (speedup 1.0000x reference)
; #define PG8_STAGE(bufoff, gbase, voff) do { _Pragma("unroll") for (int _i = 0; _i < 2; ++_i) \
;         __builtin_amdgcn_global_load_lds((const unsigned*)((const char*)(gbase) + (voff)[_i]), (PG8_LAS unsigned*)(lds + (bufoff) + ldsw + _i * 8192), 16, 0, 0); } while (0)
; #define PG8_LDA(dst, b, h) do { _Pragma("unroll") for (int m = 0; m < 4; ++m) _Pragma("unroll") for (int k = 0; k < 2; ++k) dst[m][k] = *(const PG8_LAS bf16x8*)(lds + PG8_SA(b, h) + aoff + m * 2048 + k * 1024); } while (0)
; #define PG8_LDB(dst, b, h) do { _Pragma("unroll") for (int n = 0; n < 2; ++n) _Pragma("unroll") for (int k = 0; k < 2; ++k) dst[n][k] = *(const PG8_LAS bf16x8*)(lds + PG8_SB(b, h) + boff + n * 2048 + k * 1024); } while (0)
; #define PG8_MMA(ai, bj, At, Bt) do { __builtin_amdgcn_s_setprio(1); _Pragma("unroll") for (int m = 0; m < 4; ++m) _Pragma("unroll") for (int n = 0; n < 2; ++n) _Pragma("unroll") for (int k = 0; k < 2; ++k) \
;         acc[ai][bj][m][n] = __builtin_amdgcn_mfma_f32_16x16x32_bf16(Bt[n][k], At[m][k], acc[ai][bj][m][n], 0, 0, 0); __builtin_amdgcn_s_setprio(0); } while (0)
; #define PG8_WAIT_V(n) asm volatile("s_waitcnt vmcnt(" #n ")" ::: "memory")
; #define PG8_WAIT_L(n) asm volatile("s_waitcnt lgkmcnt(" #n ")" ::: "memory")
; #define PG8_BAR __builtin_amdgcn_s_barrier()
; #define PG8_SCHED __builtin_amdgcn_sched_barrier(0)
;     ...
;             if constexpr (SP2) {
;             PG8_LDB(B0, 0, 0); PG8_LDB(B1, 0, 1); PG8_SCHED; PG8_LDA(At, 0, 0); PG8_STAGE(PG8_SA(1, 1), a1 + hstepA, voffA);
;             PG8_WAIT_V(8); PG8_WAIT_L(0); PG8_BAR; PG8_MMA(0, 0, At, B0); PG8_MMA(0, 1, At, B1); PG8_BAR; PG8_SCHED;
;             PG8_LDA(At, 0, 1); PG8_STAGE(PG8_SB(0, 0), b2, voffB); PG8_STAGE(PG8_SB(0, 1), b2 + hstep, voffB); PG8_STAGE(PG8_SA(0, 0), a2, voffA);
;             PG8_WAIT_V(8); PG8_WAIT_L(0); PG8_BAR; PG8_MMA(1, 0, At, B0); PG8_MMA(1, 1, At, B1); PG8_BAR; PG8_SCHED;
.LBB0_407:
	s_add_u32 s28, s30, 0xfff80080
	s_addc_u32 s29, s31, -1
	s_add_i32 s42, 0, 0x10000
	s_cmp_eq_u32 s93, 28
	s_cselect_b32 vcc_hi, s9, s29
	s_cselect_b32 vcc_lo, s25, s28
	v_add_u32_e32 v32, s42, v180
	s_cselect_b32 s29, s33, s50
	s_cselect_b32 s28, s40, s48
	s_add_i32 s46, 0, 0x14000
	ds_read_b128 v[136:139], v32
	ds_read_b128 v[140:143], v32 offset:1024
	ds_read_b128 v[144:147], v32 offset:2048
	ds_read_b128 v[148:151], v32 offset:3072
	v_add_u32_e32 v32, s46, v180
	ds_read_b128 v[166:169], v32
	ds_read_b128 v[170:173], v32 offset:1024
	ds_read_b128 v[174:177], v32 offset:2048
	ds_read_b128 v[198:201], v32 offset:3072
	s_add_i32 m0, s17, 0xc000
	ds_read_b128 v[202:205], v196
	ds_read_b128 v[206:209], v196 offset:1024
	ds_read_b128 v[210:213], v196 offset:2048
	ds_read_b128 v[214:217], v196 offset:3072
	ds_read_b128 v[218:221], v196 offset:4096
	ds_read_b128 v[222:225], v196 offset:5120
	ds_read_b128 v[226:229], v196 offset:6144
	ds_read_b128 v[240:243], v196 offset:7168
	global_load_lds_dwordx4 v162, s[30:31]
	s_add_i32 m0, s17, 0xe000
	s_nop 0
	global_load_lds_dwordx4 v164, s[30:31]
	s_waitcnt vmcnt(8)
	s_waitcnt lgkmcnt(0)
	s_barrier
	s_setprio 1
	s_waitcnt lgkmcnt(0)
	v_mfma_f32_16x16x32_bf16 v[132:135], v[136:139], v[202:205], v[132:135]
	v_mfma_f32_16x16x32_bf16 v[132:135], v[140:143], v[206:209], v[132:135]
	v_mfma_f32_16x16x32_bf16 v[128:131], v[148:151], v[206:209], v[128:131]
	v_mfma_f32_16x16x32_bf16 v[128:131], v[144:147], v[202:205], v[128:131]
	v_mfma_f32_16x16x32_bf16 v[112:115], v[144:147], v[210:213], v[112:115]
	v_mfma_f32_16x16x32_bf16 v[112:115], v[148:151], v[214:217], v[112:115]
	v_mfma_f32_16x16x32_bf16 v[116:119], v[140:143], v[214:217], v[116:119]
	v_mfma_f32_16x16x32_bf16 v[116:119], v[136:139], v[210:213], v[116:119]
	v_mfma_f32_16x16x32_bf16 v[100:103], v[136:139], v[218:221], v[100:103]
	v_mfma_f32_16x16x32_bf16 v[100:103], v[140:143], v[222:225], v[100:103]
	v_mfma_f32_16x16x32_bf16 v[96:99], v[148:151], v[222:225], v[96:99]
	v_mfma_f32_16x16x32_bf16 v[96:99], v[144:147], v[218:221], v[96:99]
	v_mfma_f32_16x16x32_bf16 v[80:83], v[144:147], v[226:229], v[80:83]
	v_mfma_f32_16x16x32_bf16 v[80:83], v[148:151], v[240:243], v[80:83]
	v_mfma_f32_16x16x32_bf16 v[84:87], v[140:143], v[240:243], v[84:87]
	v_mfma_f32_16x16x32_bf16 v[84:87], v[136:139], v[226:229], v[84:87]
	v_mfma_f32_16x16x32_bf16 v[76:79], v[166:169], v[226:229], v[76:79]
	v_mfma_f32_16x16x32_bf16 v[76:79], v[170:173], v[240:243], v[76:79]
	v_mfma_f32_16x16x32_bf16 v[72:75], v[198:201], v[240:243], v[72:75]
	v_mfma_f32_16x16x32_bf16 v[72:75], v[174:177], v[226:229], v[72:75]
	v_mfma_f32_16x16x32_bf16 v[88:91], v[174:177], v[218:221], v[88:91]
	v_mfma_f32_16x16x32_bf16 v[88:91], v[198:201], v[222:225], v[88:91]
	v_mfma_f32_16x16x32_bf16 v[92:95], v[170:173], v[222:225], v[92:95]
	v_mfma_f32_16x16x32_bf16 v[92:95], v[166:169], v[218:221], v[92:95]
	v_mfma_f32_16x16x32_bf16 v[108:111], v[166:169], v[210:213], v[108:111]
	v_mfma_f32_16x16x32_bf16 v[108:111], v[170:173], v[214:217], v[108:111]
	v_mfma_f32_16x16x32_bf16 v[104:107], v[198:201], v[214:217], v[104:107]
	v_mfma_f32_16x16x32_bf16 v[104:107], v[174:177], v[210:213], v[104:107]
	v_mfma_f32_16x16x32_bf16 v[120:123], v[174:177], v[202:205], v[120:123]
	v_mfma_f32_16x16x32_bf16 v[120:123], v[198:201], v[206:209], v[120:123]
	v_mfma_f32_16x16x32_bf16 v[124:127], v[170:173], v[206:209], v[124:127]
	v_mfma_f32_16x16x32_bf16 v[124:127], v[166:169], v[202:205], v[124:127]
	s_setprio 0
	s_barrier
	s_add_i32 s42, s42, s41
	v_lshl_add_u64 v[178:179], s[28:29], 0, v[154:155]
	s_mov_b32 m0, s42
	ds_read_b128 v[202:205], v196 offset:16384
	ds_read_b128 v[206:209], v196 offset:17408
	ds_read_b128 v[210:213], v196 offset:18432
	ds_read_b128 v[214:217], v196 offset:19456
	ds_read_b128 v[218:221], v196 offset:20480
	ds_read_b128 v[222:225], v196 offset:21504
	ds_read_b128 v[226:229], v196 offset:22528
	ds_read_b128 v[240:243], v196 offset:23552
	global_load_lds_dwordx4 v[178:179], off
	s_add_i32 m0, s42, 0x2000
	s_add_u32 s42, s28, 0x80000
	v_lshl_add_u64 v[186:187], s[28:29], 0, v[158:159]
	s_addc_u32 s43, s29, 0
	s_add_i32 s46, s46, s41
	global_load_lds_dwordx4 v[186:187], off
	s_mov_b32 m0, s46
	v_lshl_add_u64 v[188:189], vcc, 0, v[152:153]
	global_load_lds_dwordx4 v154, s[42:43]
	v_lshl_add_u64 v[34:35], s[42:43], 0, v[158:159]
	s_add_i32 m0, s46, 0x2000
	v_lshl_add_u64 v[190:191], vcc, 0, v[156:157]
	global_load_lds_dwordx4 v[34:35], off
	s_mov_b32 m0, s17
	s_nop 0
	global_load_lds_dwordx4 v[188:189], off
	s_mov_b32 m0, s53
	s_nop 0
	global_load_lds_dwordx4 v[190:191], off
	s_waitcnt vmcnt(8)
	s_waitcnt lgkmcnt(0)
	s_barrier
; #define PG8_STAGE(bufoff, gbase, voff) do { _Pragma("unroll") for (int _i = 0; _i < 2; ++_i) \
;         __builtin_amdgcn_global_load_lds((const unsigned*)((const char*)(gbase) + (voff)[_i]), (PG8_LAS unsigned*)(lds + (bufoff) + ldsw + _i * 8192), 16, 0, 0); } while (0)
; #define PG8_LDA(dst, b, h) do { _Pragma("unroll") for (int m = 0; m < 4; ++m) _Pragma("unroll") for (int k = 0; k < 2; ++k) dst[m][k] = *(const PG8_LAS bf16x8*)(lds + PG8_SA(b, h) + aoff + m * 2048 + k * 1024); } while (0)
; #define PG8_LDB(dst, b, h) do { _Pragma("unroll") for (int n = 0; n < 2; ++n) _Pragma("unroll") for (int k = 0; k < 2; ++k) dst[n][k] = *(const PG8_LAS bf16x8*)(lds + PG8_SB(b, h) + boff + n * 2048 + k * 1024); } while (0)
; #define PG8_MMA(ai, bj, At, Bt) do { __builtin_amdgcn_s_setprio(1); _Pragma("unroll") for (int m = 0; m < 4; ++m) _Pragma("unroll") for (int n = 0; n < 2; ++n) _Pragma("unroll") for (int k = 0; k < 2; ++k) \
;         acc[ai][bj][m][n] = __builtin_amdgcn_mfma_f32_16x16x32_bf16(Bt[n][k], At[m][k], acc[ai][bj][m][n], 0, 0, 0); __builtin_amdgcn_s_setprio(0); } while (0)
; #define PG8_WAIT_V(n) asm volatile("s_waitcnt vmcnt(" #n ")" ::: "memory")
; #define PG8_WAIT_L(n) asm volatile("s_waitcnt lgkmcnt(" #n ")" ::: "memory")
; #define PG8_BAR __builtin_amdgcn_s_barrier()
; #define PG8_SCHED __builtin_amdgcn_sched_barrier(0)
;     ...
;             PG8_WAIT_V(8); PG8_WAIT_L(0); PG8_BAR; PG8_MMA(1, 0, At, B0); PG8_MMA(1, 1, At, B1); PG8_BAR; PG8_SCHED;
;             PG8_LDB(B0, 1, 0); PG8_LDB(B1, 1, 1); PG8_SCHED; PG8_LDA(At, 1, 0); PG8_STAGE(PG8_SA(0, 1), a2 + hstepA, voffA);
;             PG8_WAIT_V(8); PG8_WAIT_L(0); PG8_BAR; PG8_MMA(0, 0, At, B0); PG8_MMA(0, 1, At, B1); PG8_BAR; PG8_SCHED;
	s_setprio 1
	s_waitcnt lgkmcnt(0)
	v_mfma_f32_16x16x32_bf16 v[68:71], v[136:139], v[202:205], v[68:71]
	v_mfma_f32_16x16x32_bf16 v[68:71], v[140:143], v[206:209], v[68:71]
	v_mfma_f32_16x16x32_bf16 v[64:67], v[148:151], v[206:209], v[64:67]
	v_mfma_f32_16x16x32_bf16 v[64:67], v[144:147], v[202:205], v[64:67]
	v_mfma_f32_16x16x32_bf16 v[48:51], v[144:147], v[210:213], v[48:51]
	v_mfma_f32_16x16x32_bf16 v[48:51], v[148:151], v[214:217], v[48:51]
	v_mfma_f32_16x16x32_bf16 v[52:55], v[140:143], v[214:217], v[52:55]
	v_mfma_f32_16x16x32_bf16 v[52:55], v[136:139], v[210:213], v[52:55]
	v_mfma_f32_16x16x32_bf16 v[34:37], v[136:139], v[218:221], v[36:39]
	v_mfma_f32_16x16x32_bf16 v[34:37], v[140:143], v[222:225], v[34:37]
	v_mfma_f32_16x16x32_bf16 v[26:29], v[148:151], v[222:225], v[26:29]
	v_mfma_f32_16x16x32_bf16 v[26:29], v[144:147], v[218:221], v[26:29]
	v_mfma_f32_16x16x32_bf16 v[10:13], v[144:147], v[226:229], v[10:13]
	v_mfma_f32_16x16x32_bf16 v[10:13], v[148:151], v[240:243], v[10:13]
	v_mfma_f32_16x16x32_bf16 v[14:17], v[140:143], v[240:243], v[14:17]
	v_mfma_f32_16x16x32_bf16 v[14:17], v[136:139], v[226:229], v[14:17]
	v_mfma_f32_16x16x32_bf16 v[6:9], v[166:169], v[226:229], v[6:9]
	v_mfma_f32_16x16x32_bf16 v[6:9], v[170:173], v[240:243], v[6:9]
	v_mfma_f32_16x16x32_bf16 v[2:5], v[198:201], v[240:243], v[2:5]
	v_mfma_f32_16x16x32_bf16 v[2:5], v[174:177], v[226:229], v[2:5]
	v_mfma_f32_16x16x32_bf16 v[18:21], v[174:177], v[218:221], v[18:21]
	v_mfma_f32_16x16x32_bf16 v[18:21], v[198:201], v[222:225], v[18:21]
	v_mfma_f32_16x16x32_bf16 v[22:25], v[170:173], v[222:225], v[22:25]
	v_mfma_f32_16x16x32_bf16 v[22:25], v[166:169], v[218:221], v[22:25]
	v_mfma_f32_16x16x32_bf16 v[44:47], v[166:169], v[210:213], v[44:47]
	v_mfma_f32_16x16x32_bf16 v[44:47], v[170:173], v[214:217], v[44:47]
	v_mfma_f32_16x16x32_bf16 v[40:43], v[198:201], v[214:217], v[40:43]
	v_mfma_f32_16x16x32_bf16 v[40:43], v[174:177], v[210:213], v[40:43]
	v_mfma_f32_16x16x32_bf16 v[56:59], v[174:177], v[202:205], v[56:59]
	v_mfma_f32_16x16x32_bf16 v[56:59], v[198:201], v[206:209], v[56:59]
	v_mfma_f32_16x16x32_bf16 v[60:63], v[170:173], v[206:209], v[60:63]
	v_mfma_f32_16x16x32_bf16 v[60:63], v[166:169], v[202:205], v[60:63]
	s_setprio 0
	s_barrier
	s_add_i32 s46, 0, 0x18000
	v_add_u32_e32 v32, s46, v180
	s_add_i32 s47, 0, 0x1c000
	ds_read_b128 v[136:139], v32
	ds_read_b128 v[140:143], v32 offset:1024
	ds_read_b128 v[144:147], v32 offset:2048
	ds_read_b128 v[148:151], v32 offset:3072
	v_add_u32_e32 v32, s47, v180
	ds_read_b128 v[166:169], v32
	ds_read_b128 v[170:173], v32 offset:1024
	ds_read_b128 v[174:177], v32 offset:2048
	ds_read_b128 v[198:201], v32 offset:3072
	s_add_u32 s42, vcc_lo, 0x80000
	s_addc_u32 s43, vcc_hi, 0
	s_mov_b32 m0, s74
	ds_read_b128 v[202:205], v196 offset:32768
	ds_read_b128 v[206:209], v196 offset:33792
	ds_read_b128 v[210:213], v196 offset:34816
	ds_read_b128 v[214:217], v196 offset:35840
	ds_read_b128 v[218:221], v196 offset:36864
	ds_read_b128 v[222:225], v196 offset:37888
	ds_read_b128 v[226:229], v196 offset:38912
	ds_read_b128 v[240:243], v196 offset:39936
	global_load_lds_dwordx4 v152, s[42:43]
	s_mov_b32 m0, s78
	s_nop 0
	global_load_lds_dwordx4 v156, s[42:43]
	s_waitcnt vmcnt(8)
	s_waitcnt lgkmcnt(0)
	s_barrier
	s_setprio 1
	s_waitcnt lgkmcnt(0)
	v_mfma_f32_16x16x32_bf16 v[132:135], v[136:139], v[202:205], v[132:135]
	v_mfma_f32_16x16x32_bf16 v[132:135], v[140:143], v[206:209], v[132:135]
	v_mfma_f32_16x16x32_bf16 v[128:131], v[148:151], v[206:209], v[128:131]
	v_mfma_f32_16x16x32_bf16 v[128:131], v[144:147], v[202:205], v[128:131]
	v_mfma_f32_16x16x32_bf16 v[112:115], v[144:147], v[210:213], v[112:115]
	v_mfma_f32_16x16x32_bf16 v[112:115], v[148:151], v[214:217], v[112:115]
	v_mfma_f32_16x16x32_bf16 v[116:119], v[140:143], v[214:217], v[116:119]
	v_mfma_f32_16x16x32_bf16 v[116:119], v[136:139], v[210:213], v[116:119]
	v_mfma_f32_16x16x32_bf16 v[100:103], v[136:139], v[218:221], v[100:103]
	v_mfma_f32_16x16x32_bf16 v[100:103], v[140:143], v[222:225], v[100:103]
	v_mfma_f32_16x16x32_bf16 v[96:99], v[148:151], v[222:225], v[96:99]
	v_mfma_f32_16x16x32_bf16 v[96:99], v[144:147], v[218:221], v[96:99]
	v_mfma_f32_16x16x32_bf16 v[80:83], v[144:147], v[226:229], v[80:83]
	v_mfma_f32_16x16x32_bf16 v[80:83], v[148:151], v[240:243], v[80:83]
	v_mfma_f32_16x16x32_bf16 v[84:87], v[140:143], v[240:243], v[84:87]
	v_mfma_f32_16x16x32_bf16 v[84:87], v[136:139], v[226:229], v[84:87]
	v_mfma_f32_16x16x32_bf16 v[76:79], v[166:169], v[226:229], v[76:79]
	v_mfma_f32_16x16x32_bf16 v[76:79], v[170:173], v[240:243], v[76:79]
	v_mfma_f32_16x16x32_bf16 v[72:75], v[198:201], v[240:243], v[72:75]
	v_mfma_f32_16x16x32_bf16 v[72:75], v[174:177], v[226:229], v[72:75]
	v_mfma_f32_16x16x32_bf16 v[88:91], v[174:177], v[218:221], v[88:91]
	v_mfma_f32_16x16x32_bf16 v[88:91], v[198:201], v[222:225], v[88:91]
	v_mfma_f32_16x16x32_bf16 v[92:95], v[170:173], v[222:225], v[92:95]
	v_mfma_f32_16x16x32_bf16 v[92:95], v[166:169], v[218:221], v[92:95]
	v_mfma_f32_16x16x32_bf16 v[108:111], v[166:169], v[210:213], v[108:111]
	v_mfma_f32_16x16x32_bf16 v[108:111], v[170:173], v[214:217], v[108:111]
	v_mfma_f32_16x16x32_bf16 v[104:107], v[198:201], v[214:217], v[104:107]
	v_mfma_f32_16x16x32_bf16 v[104:107], v[174:177], v[210:213], v[104:107]
	v_mfma_f32_16x16x32_bf16 v[120:123], v[174:177], v[202:205], v[120:123]
	v_mfma_f32_16x16x32_bf16 v[120:123], v[198:201], v[206:209], v[120:123]
	v_mfma_f32_16x16x32_bf16 v[124:127], v[170:173], v[206:209], v[124:127]
	v_mfma_f32_16x16x32_bf16 v[124:127], v[166:169], v[202:205], v[124:127]
	s_setprio 0
	s_barrier
; #define PG8_STAGE(bufoff, gbase, voff) do { _Pragma("unroll") for (int _i = 0; _i < 2; ++_i) \
;         __builtin_amdgcn_global_load_lds((const unsigned*)((const char*)(gbase) + (voff)[_i]), (PG8_LAS unsigned*)(lds + (bufoff) + ldsw + _i * 8192), 16, 0, 0); } while (0)
; #define PG8_LDA(dst, b, h) do { _Pragma("unroll") for (int m = 0; m < 4; ++m) _Pragma("unroll") for (int k = 0; k < 2; ++k) dst[m][k] = *(const PG8_LAS bf16x8*)(lds + PG8_SA(b, h) + aoff + m * 2048 + k * 1024); } while (0)
; #define PG8_MMA(ai, bj, At, Bt) do { __builtin_amdgcn_s_setprio(1); _Pragma("unroll") for (int m = 0; m < 4; ++m) _Pragma("unroll") for (int n = 0; n < 2; ++n) _Pragma("unroll") for (int k = 0; k < 2; ++k) \
;         acc[ai][bj][m][n] = __builtin_amdgcn_mfma_f32_16x16x32_bf16(Bt[n][k], At[m][k], acc[ai][bj][m][n], 0, 0, 0); __builtin_amdgcn_s_setprio(0); } while (0)
; #define PG8_WAIT_V(n) asm volatile("s_waitcnt vmcnt(" #n ")" ::: "memory")
; #define PG8_WAIT_L(n) asm volatile("s_waitcnt lgkmcnt(" #n ")" ::: "memory")
; #define PG8_BAR __builtin_amdgcn_s_barrier()
; #define PG8_SCHED __builtin_amdgcn_sched_barrier(0)
;     ...
;         for (int t = 0; t < nt; t += 2) {
;             const bool last = (t == nt - 2);
;             const char* a1 = cA + (size_t)(t + 1) * kstep;
;             const char* a2 = last ? nA : cA + (size_t)(t + 2) * kstep; const char* b2 = last ? nB : cB + (size_t)(t + 2) * kstep;
;     ...
;             PG8_LDA(At, 1, 1); PG8_STAGE(PG8_SB(1, 0), b3, voffB); PG8_STAGE(PG8_SB(1, 1), b3 + hstep, voffB); PG8_STAGE(PG8_SA(1, 0), a3, voffA);
;             PG8_WAIT_V(8); PG8_WAIT_L(0); PG8_BAR; PG8_MMA(1, 0, At, B0); PG8_MMA(1, 1, At, B1); PG8_BAR; PG8_SCHED;
	s_add_i32 s42, s46, s41
	v_lshl_add_u64 v[38:39], v[178:179], 0, s[64:65]
	s_mov_b32 m0, s42
	ds_read_b128 v[202:205], v196 offset:49152
	ds_read_b128 v[206:209], v196 offset:50176
	ds_read_b128 v[210:213], v196 offset:51200
	ds_read_b128 v[214:217], v196 offset:52224
	ds_read_b128 v[218:221], v196 offset:53248
	ds_read_b128 v[222:225], v196 offset:54272
	ds_read_b128 v[226:229], v196 offset:55296
	ds_read_b128 v[240:243], v196 offset:56320
	global_load_lds_dwordx4 v[38:39], off
	s_add_i32 m0, s42, 0x2000
	s_add_u32 s28, s28, 0x80080
	v_lshl_add_u64 v[38:39], v[186:187], 0, s[64:65]
	s_addc_u32 s29, s29, 0
	s_add_i32 s42, s47, s41
	global_load_lds_dwordx4 v[38:39], off
	s_mov_b32 m0, s42
	s_nop 0
	global_load_lds_dwordx4 v154, s[28:29]
	s_add_i32 m0, s42, 0x2000
	s_nop 0
	global_load_lds_dwordx4 v158, s[28:29]
	v_lshl_add_u64 v[38:39], v[188:189], 0, s[64:65]
	s_mov_b32 m0, s79
	s_nop 0
	global_load_lds_dwordx4 v[38:39], off
	v_lshl_add_u64 v[38:39], v[190:191], 0, s[64:65]
	s_mov_b32 m0, s4
	s_nop 0
	global_load_lds_dwordx4 v[38:39], off
	s_waitcnt vmcnt(8)
	s_waitcnt lgkmcnt(0)
	s_barrier
	s_setprio 1
	s_waitcnt lgkmcnt(0)
	v_mfma_f32_16x16x32_bf16 v[68:71], v[136:139], v[202:205], v[68:71]
	v_mfma_f32_16x16x32_bf16 v[68:71], v[140:143], v[206:209], v[68:71]
	v_mfma_f32_16x16x32_bf16 v[64:67], v[148:151], v[206:209], v[64:67]
	v_mfma_f32_16x16x32_bf16 v[64:67], v[144:147], v[202:205], v[64:67]
	v_mfma_f32_16x16x32_bf16 v[48:51], v[144:147], v[210:213], v[48:51]
	v_mfma_f32_16x16x32_bf16 v[48:51], v[148:151], v[214:217], v[48:51]
	v_mfma_f32_16x16x32_bf16 v[52:55], v[140:143], v[214:217], v[52:55]
	v_mfma_f32_16x16x32_bf16 v[52:55], v[136:139], v[210:213], v[52:55]
	v_mfma_f32_16x16x32_bf16 v[34:37], v[136:139], v[218:221], v[34:37]
	v_mfma_f32_16x16x32_bf16 v[36:39], v[140:143], v[222:225], v[34:37]
	v_mfma_f32_16x16x32_bf16 v[26:29], v[148:151], v[222:225], v[26:29]
	v_mfma_f32_16x16x32_bf16 v[26:29], v[144:147], v[218:221], v[26:29]
	v_mfma_f32_16x16x32_bf16 v[10:13], v[144:147], v[226:229], v[10:13]
	v_mfma_f32_16x16x32_bf16 v[10:13], v[148:151], v[240:243], v[10:13]
	v_mfma_f32_16x16x32_bf16 v[14:17], v[140:143], v[240:243], v[14:17]
	v_mfma_f32_16x16x32_bf16 v[14:17], v[136:139], v[226:229], v[14:17]
	v_mfma_f32_16x16x32_bf16 v[6:9], v[166:169], v[226:229], v[6:9]
	v_mfma_f32_16x16x32_bf16 v[6:9], v[170:173], v[240:243], v[6:9]
	v_mfma_f32_16x16x32_bf16 v[2:5], v[198:201], v[240:243], v[2:5]
	v_mfma_f32_16x16x32_bf16 v[2:5], v[174:177], v[226:229], v[2:5]
	v_mfma_f32_16x16x32_bf16 v[18:21], v[174:177], v[218:221], v[18:21]
	v_mfma_f32_16x16x32_bf16 v[18:21], v[198:201], v[222:225], v[18:21]
	v_mfma_f32_16x16x32_bf16 v[22:25], v[170:173], v[222:225], v[22:25]
	v_mfma_f32_16x16x32_bf16 v[22:25], v[166:169], v[218:221], v[22:25]
	v_mfma_f32_16x16x32_bf16 v[44:47], v[166:169], v[210:213], v[44:47]
	v_mfma_f32_16x16x32_bf16 v[44:47], v[170:173], v[214:217], v[44:47]
	v_mfma_f32_16x16x32_bf16 v[40:43], v[198:201], v[214:217], v[40:43]
	v_mfma_f32_16x16x32_bf16 v[40:43], v[174:177], v[210:213], v[40:43]
	v_mfma_f32_16x16x32_bf16 v[56:59], v[174:177], v[202:205], v[56:59]
	v_mfma_f32_16x16x32_bf16 v[56:59], v[198:201], v[206:209], v[56:59]
	v_mfma_f32_16x16x32_bf16 v[60:63], v[170:173], v[206:209], v[60:63]
	v_mfma_f32_16x16x32_bf16 v[60:63], v[166:169], v[202:205], v[60:63]
	s_setprio 0
	s_barrier
	s_add_i32 s93, s93, 2
	s_add_u32 s30, s30, 0x100
	s_addc_u32 s31, s31, 0
	s_add_u32 s48, s48, 0x100
	s_addc_u32 s50, s50, 0
	s_cmp_gt_u32 s93, 29
	s_cbranch_scc0 .LBB0_407
	s_and_b64 vcc, exec, s[60:61]
	s_cbranch_vccz .LBB0_410
	s_barrier

; #define PG8_STAGE(bufoff, gbase, voff) do { _Pragma("unroll") for (int _i = 0; _i < 2; ++_i) \
;         __builtin_amdgcn_global_load_lds((const unsigned*)((const char*)(gbase) + (voff)[_i]), (PG8_LAS unsigned*)(lds + (bufoff) + ldsw + _i * 8192), 16, 0, 0); } while (0)
; #define PG8_LDA(dst, b, h) do { _Pragma("unroll") for (int m = 0; m < 4; ++m) _Pragma("unroll") for (int k = 0; k < 2; ++k) dst[m][k] = *(const PG8_LAS bf16x8*)(lds + PG8_SA(b, h) + aoff + m * 2048 + k * 1024); } while (0)
; #define PG8_LDB(dst, b, h) do { _Pragma("unroll") for (int n = 0; n < 2; ++n) _Pragma("unroll") for (int k = 0; k < 2; ++k) dst[n][k] = *(const PG8_LAS bf16x8*)(lds + PG8_SB(b, h) + boff + n * 2048 + k * 1024); } while (0)
; #define PG8_MMA(ai, bj, At, Bt) do { __builtin_amdgcn_s_setprio(1); _Pragma("unroll") for (int m = 0; m < 4; ++m) _Pragma("unroll") for (int n = 0; n < 2; ++n) _Pragma("unroll") for (int k = 0; k < 2; ++k) \
;         acc[ai][bj][m][n] = __builtin_amdgcn_mfma_f32_16x16x32_bf16(Bt[n][k], At[m][k], acc[ai][bj][m][n], 0, 0, 0); __builtin_amdgcn_s_setprio(0); } while (0)
; #define PG8_WAIT_V(n) asm volatile("s_waitcnt vmcnt(" #n ")" ::: "memory")
; #define PG8_WAIT_L(n) asm volatile("s_waitcnt lgkmcnt(" #n ")" ::: "memory")
; #define PG8_BAR __builtin_amdgcn_s_barrier()
; #define PG8_SCHED __builtin_amdgcn_sched_barrier(0)
;     ...
;             if constexpr (SP2) {
;             PG8_LDB(B0, 0, 0); PG8_LDB(B1, 0, 1); PG8_SCHED; PG8_LDA(At, 0, 0); PG8_STAGE(PG8_SA(1, 1), a1 + hstepA, voffA);
;             PG8_WAIT_V(8); PG8_WAIT_L(0); PG8_BAR; PG8_MMA(0, 0, At, B0); PG8_MMA(0, 1, At, B1); PG8_BAR; PG8_SCHED;
;             PG8_LDA(At, 0, 1); PG8_STAGE(PG8_SB(0, 0), b2, voffB); PG8_STAGE(PG8_SB(0, 1), b2 + hstep, voffB); PG8_STAGE(PG8_SA(0, 0), a2, voffA);
;             PG8_WAIT_V(8); PG8_WAIT_L(0); PG8_BAR; PG8_MMA(1, 0, At, B0); PG8_MMA(1, 1, At, B1); PG8_BAR; PG8_SCHED;
.LBB0_748:
	s_add_u32 s4, s18, 0x100
	s_addc_u32 s5, s19, 0
	s_add_i32 s42, 0, 0x10000
	s_cmp_eq_u32 s78, 4
	s_cselect_b32 s27, s13, s5
	s_cselect_b32 s26, s12, s4
	v_add_u32_e32 v153, s42, v150
	s_cselect_b32 s25, s11, s74
	s_cselect_b32 s24, s33, s48
	s_add_i32 s43, 0, 0x14000
	ds_read_b128 v[142:145], v153
	ds_read_b128 v[146:149], v153 offset:1024
	ds_read_b128 v[154:157], v153 offset:2048
	ds_read_b128 v[158:161], v153 offset:3072
	v_add_u32_e32 v153, s43, v150
	ds_read_b128 v[162:165], v153
	ds_read_b128 v[166:169], v153 offset:1024
	ds_read_b128 v[170:173], v153 offset:2048
	ds_read_b128 v[174:177], v153 offset:3072
	s_add_i32 m0, s17, 0xc000
	ds_read_b128 v[178:181], v152
	ds_read_b128 v[196:199], v152 offset:1024
	ds_read_b128 v[200:203], v152 offset:2048
	ds_read_b128 v[204:207], v152 offset:3072
	ds_read_b128 v[208:211], v152 offset:4096
	ds_read_b128 v[212:215], v152 offset:5120
	ds_read_b128 v[216:219], v152 offset:6144
	ds_read_b128 v[220:223], v152 offset:7168
	global_load_lds_dwordx4 v138, s[18:19]
	s_add_i32 m0, s17, 0xe000
	s_nop 0
	global_load_lds_dwordx4 v140, s[18:19]
	s_waitcnt vmcnt(8)
	s_waitcnt lgkmcnt(0)
	s_barrier
	s_setprio 1
	s_waitcnt lgkmcnt(0)
	v_mfma_f32_16x16x32_bf16 v[130:133], v[142:145], v[178:181], v[130:133]
	v_mfma_f32_16x16x32_bf16 v[130:133], v[146:149], v[196:199], v[130:133]
	v_mfma_f32_16x16x32_bf16 v[126:129], v[158:161], v[196:199], v[126:129]
	v_mfma_f32_16x16x32_bf16 v[126:129], v[154:157], v[178:181], v[126:129]
	v_mfma_f32_16x16x32_bf16 v[110:113], v[154:157], v[200:203], v[110:113]
	v_mfma_f32_16x16x32_bf16 v[110:113], v[158:161], v[204:207], v[110:113]
	v_mfma_f32_16x16x32_bf16 v[114:117], v[146:149], v[204:207], v[114:117]
	v_mfma_f32_16x16x32_bf16 v[114:117], v[142:145], v[200:203], v[114:117]
	v_mfma_f32_16x16x32_bf16 v[98:101], v[142:145], v[208:211], v[98:101]
	v_mfma_f32_16x16x32_bf16 v[98:101], v[146:149], v[212:215], v[98:101]
	v_mfma_f32_16x16x32_bf16 v[94:97], v[158:161], v[212:215], v[94:97]
	v_mfma_f32_16x16x32_bf16 v[94:97], v[154:157], v[208:211], v[94:97]
	v_mfma_f32_16x16x32_bf16 v[78:81], v[154:157], v[216:219], v[78:81]
	v_mfma_f32_16x16x32_bf16 v[78:81], v[158:161], v[220:223], v[78:81]
	v_mfma_f32_16x16x32_bf16 v[82:85], v[146:149], v[220:223], v[82:85]
	v_mfma_f32_16x16x32_bf16 v[82:85], v[142:145], v[216:219], v[82:85]
	v_mfma_f32_16x16x32_bf16 v[74:77], v[162:165], v[216:219], v[74:77]
	v_mfma_f32_16x16x32_bf16 v[74:77], v[166:169], v[220:223], v[74:77]
	v_mfma_f32_16x16x32_bf16 v[70:73], v[174:177], v[220:223], v[70:73]
	v_mfma_f32_16x16x32_bf16 v[70:73], v[170:173], v[216:219], v[70:73]
	v_mfma_f32_16x16x32_bf16 v[86:89], v[170:173], v[208:211], v[86:89]
	v_mfma_f32_16x16x32_bf16 v[86:89], v[174:177], v[212:215], v[86:89]
	v_mfma_f32_16x16x32_bf16 v[90:93], v[166:169], v[212:215], v[90:93]
	v_mfma_f32_16x16x32_bf16 v[90:93], v[162:165], v[208:211], v[90:93]
	v_mfma_f32_16x16x32_bf16 v[106:109], v[162:165], v[200:203], v[106:109]
	v_mfma_f32_16x16x32_bf16 v[106:109], v[166:169], v[204:207], v[106:109]
	v_mfma_f32_16x16x32_bf16 v[102:105], v[174:177], v[204:207], v[102:105]
	v_mfma_f32_16x16x32_bf16 v[102:105], v[170:173], v[200:203], v[102:105]
	v_mfma_f32_16x16x32_bf16 v[118:121], v[170:173], v[178:181], v[118:121]
	v_mfma_f32_16x16x32_bf16 v[118:121], v[174:177], v[196:199], v[118:121]
	v_mfma_f32_16x16x32_bf16 v[122:125], v[166:169], v[196:199], v[122:125]
	v_mfma_f32_16x16x32_bf16 v[122:125], v[162:165], v[178:181], v[122:125]
	s_setprio 0
	s_barrier
	s_add_i32 s18, s42, s30
	v_lshl_add_u64 v[182:183], s[24:25], 0, v[32:33]
	s_mov_b32 m0, s18
	ds_read_b128 v[178:181], v152 offset:16384
	ds_read_b128 v[196:199], v152 offset:17408
	ds_read_b128 v[200:203], v152 offset:18432
	ds_read_b128 v[204:207], v152 offset:19456
	ds_read_b128 v[208:211], v152 offset:20480
	ds_read_b128 v[212:215], v152 offset:21504
	ds_read_b128 v[216:219], v152 offset:22528
	ds_read_b128 v[220:223], v152 offset:23552
	global_load_lds_dwordx4 v[182:183], off
	s_add_i32 m0, s18, 0x2000
	s_add_u32 s18, s24, 0x20000
	v_lshl_add_u64 v[186:187], s[24:25], 0, v[136:137]
	s_addc_u32 s19, s25, 0
	s_add_i32 s42, s43, s30
	global_load_lds_dwordx4 v[186:187], off
	s_mov_b32 m0, s42
	v_lshl_add_u64 v[190:191], s[26:27], 0, v[134:135]
	global_load_lds_dwordx4 v32, s[18:19]
	s_add_i32 m0, s42, 0x2000
	s_nop 0
	global_load_lds_dwordx4 v136, s[18:19]
	v_lshl_add_u64 v[188:189], s[26:27], 0, v[30:31]
	s_mov_b32 m0, s17
	s_nop 0
	global_load_lds_dwordx4 v[188:189], off
	s_mov_b32 m0, s31
	s_nop 0
	global_load_lds_dwordx4 v[190:191], off
	s_waitcnt vmcnt(8)
	s_waitcnt lgkmcnt(0)
	s_barrier
; #define PG8_STAGE(bufoff, gbase, voff) do { _Pragma("unroll") for (int _i = 0; _i < 2; ++_i) \
;         __builtin_amdgcn_global_load_lds((const unsigned*)((const char*)(gbase) + (voff)[_i]), (PG8_LAS unsigned*)(lds + (bufoff) + ldsw + _i * 8192), 16, 0, 0); } while (0)
; #define PG8_LDA(dst, b, h) do { _Pragma("unroll") for (int m = 0; m < 4; ++m) _Pragma("unroll") for (int k = 0; k < 2; ++k) dst[m][k] = *(const PG8_LAS bf16x8*)(lds + PG8_SA(b, h) + aoff + m * 2048 + k * 1024); } while (0)
; #define PG8_LDB(dst, b, h) do { _Pragma("unroll") for (int n = 0; n < 2; ++n) _Pragma("unroll") for (int k = 0; k < 2; ++k) dst[n][k] = *(const PG8_LAS bf16x8*)(lds + PG8_SB(b, h) + boff + n * 2048 + k * 1024); } while (0)
; #define PG8_MMA(ai, bj, At, Bt) do { __builtin_amdgcn_s_setprio(1); _Pragma("unroll") for (int m = 0; m < 4; ++m) _Pragma("unroll") for (int n = 0; n < 2; ++n) _Pragma("unroll") for (int k = 0; k < 2; ++k) \
;         acc[ai][bj][m][n] = __builtin_amdgcn_mfma_f32_16x16x32_bf16(Bt[n][k], At[m][k], acc[ai][bj][m][n], 0, 0, 0); __builtin_amdgcn_s_setprio(0); } while (0)
; #define PG8_WAIT_V(n) asm volatile("s_waitcnt vmcnt(" #n ")" ::: "memory")
; #define PG8_WAIT_L(n) asm volatile("s_waitcnt lgkmcnt(" #n ")" ::: "memory")
; #define PG8_BAR __builtin_amdgcn_s_barrier()
; #define PG8_SCHED __builtin_amdgcn_sched_barrier(0)
;     ...
;             PG8_WAIT_V(8); PG8_WAIT_L(0); PG8_BAR; PG8_MMA(1, 0, At, B0); PG8_MMA(1, 1, At, B1); PG8_BAR; PG8_SCHED;
;             PG8_LDB(B0, 1, 0); PG8_LDB(B1, 1, 1); PG8_SCHED; PG8_LDA(At, 1, 0); PG8_STAGE(PG8_SA(0, 1), a2 + hstepA, voffA);
;             PG8_WAIT_V(8); PG8_WAIT_L(0); PG8_BAR; PG8_MMA(0, 0, At, B0); PG8_MMA(0, 1, At, B1); PG8_BAR; PG8_SCHED;
	s_setprio 1
	s_waitcnt lgkmcnt(0)
	v_mfma_f32_16x16x32_bf16 v[66:69], v[142:145], v[178:181], v[66:69]
	v_mfma_f32_16x16x32_bf16 v[66:69], v[146:149], v[196:199], v[66:69]
	v_mfma_f32_16x16x32_bf16 v[62:65], v[158:161], v[196:199], v[62:65]
	v_mfma_f32_16x16x32_bf16 v[62:65], v[154:157], v[178:181], v[62:65]
	v_mfma_f32_16x16x32_bf16 v[46:49], v[154:157], v[200:203], v[46:49]
	v_mfma_f32_16x16x32_bf16 v[46:49], v[158:161], v[204:207], v[46:49]
	v_mfma_f32_16x16x32_bf16 v[50:53], v[146:149], v[204:207], v[50:53]
	v_mfma_f32_16x16x32_bf16 v[50:53], v[142:145], v[200:203], v[50:53]
	v_mfma_f32_16x16x32_bf16 v[34:37], v[142:145], v[208:211], v[34:37]
	v_mfma_f32_16x16x32_bf16 v[34:37], v[146:149], v[212:215], v[34:37]
	v_mfma_f32_16x16x32_bf16 v[26:29], v[158:161], v[212:215], v[26:29]
	v_mfma_f32_16x16x32_bf16 v[26:29], v[154:157], v[208:211], v[26:29]
	v_mfma_f32_16x16x32_bf16 v[10:13], v[154:157], v[216:219], v[10:13]
	v_mfma_f32_16x16x32_bf16 v[10:13], v[158:161], v[220:223], v[10:13]
	v_mfma_f32_16x16x32_bf16 v[14:17], v[146:149], v[220:223], v[14:17]
	v_mfma_f32_16x16x32_bf16 v[14:17], v[142:145], v[216:219], v[14:17]
	v_mfma_f32_16x16x32_bf16 v[6:9], v[162:165], v[216:219], v[6:9]
	v_mfma_f32_16x16x32_bf16 v[6:9], v[166:169], v[220:223], v[6:9]
	v_mfma_f32_16x16x32_bf16 v[2:5], v[174:177], v[220:223], v[2:5]
	v_mfma_f32_16x16x32_bf16 v[2:5], v[170:173], v[216:219], v[2:5]
	v_mfma_f32_16x16x32_bf16 v[18:21], v[170:173], v[208:211], v[18:21]
	v_mfma_f32_16x16x32_bf16 v[18:21], v[174:177], v[212:215], v[18:21]
	v_mfma_f32_16x16x32_bf16 v[22:25], v[166:169], v[212:215], v[22:25]
	v_mfma_f32_16x16x32_bf16 v[22:25], v[162:165], v[208:211], v[22:25]
	v_mfma_f32_16x16x32_bf16 v[42:45], v[162:165], v[200:203], v[42:45]
	v_mfma_f32_16x16x32_bf16 v[42:45], v[166:169], v[204:207], v[42:45]
	v_mfma_f32_16x16x32_bf16 v[38:41], v[174:177], v[204:207], v[38:41]
	v_mfma_f32_16x16x32_bf16 v[38:41], v[170:173], v[200:203], v[38:41]
	v_mfma_f32_16x16x32_bf16 v[54:57], v[170:173], v[178:181], v[54:57]
	v_mfma_f32_16x16x32_bf16 v[54:57], v[174:177], v[196:199], v[54:57]
	v_mfma_f32_16x16x32_bf16 v[58:61], v[166:169], v[196:199], v[58:61]
	v_mfma_f32_16x16x32_bf16 v[58:61], v[162:165], v[178:181], v[58:61]
	s_setprio 0
	s_barrier
	s_add_i32 s42, 0, 0x18000
	v_add_u32_e32 v153, s42, v150
	s_add_i32 s43, 0, 0x1c000
	ds_read_b128 v[142:145], v153
	ds_read_b128 v[146:149], v153 offset:1024
	ds_read_b128 v[154:157], v153 offset:2048
	ds_read_b128 v[158:161], v153 offset:3072
	v_add_u32_e32 v153, s43, v150
	ds_read_b128 v[162:165], v153
	ds_read_b128 v[166:169], v153 offset:1024
	ds_read_b128 v[170:173], v153 offset:2048
	ds_read_b128 v[174:177], v153 offset:3072
	s_add_u32 s18, s26, 0xf0000
	s_addc_u32 s19, s27, 0
	s_mov_b32 m0, s38
	ds_read_b128 v[178:181], v152 offset:32768
	ds_read_b128 v[196:199], v152 offset:33792
	ds_read_b128 v[200:203], v152 offset:34816
	ds_read_b128 v[204:207], v152 offset:35840
	ds_read_b128 v[208:211], v152 offset:36864
	ds_read_b128 v[212:215], v152 offset:37888
	ds_read_b128 v[216:219], v152 offset:38912
	ds_read_b128 v[220:223], v152 offset:39936
	global_load_lds_dwordx4 v30, s[18:19]
	v_lshl_add_u64 v[224:225], s[18:19], 0, v[134:135]
	s_mov_b32 m0, s39
	s_nop 0
	global_load_lds_dwordx4 v[224:225], off
	s_waitcnt vmcnt(8)
	s_waitcnt lgkmcnt(0)
	s_barrier
	s_setprio 1
	s_waitcnt lgkmcnt(0)
	v_mfma_f32_16x16x32_bf16 v[130:133], v[142:145], v[178:181], v[130:133]
	v_mfma_f32_16x16x32_bf16 v[130:133], v[146:149], v[196:199], v[130:133]
	v_mfma_f32_16x16x32_bf16 v[126:129], v[158:161], v[196:199], v[126:129]
	v_mfma_f32_16x16x32_bf16 v[126:129], v[154:157], v[178:181], v[126:129]
	v_mfma_f32_16x16x32_bf16 v[110:113], v[154:157], v[200:203], v[110:113]
	v_mfma_f32_16x16x32_bf16 v[110:113], v[158:161], v[204:207], v[110:113]
	v_mfma_f32_16x16x32_bf16 v[114:117], v[146:149], v[204:207], v[114:117]
	v_mfma_f32_16x16x32_bf16 v[114:117], v[142:145], v[200:203], v[114:117]
	v_mfma_f32_16x16x32_bf16 v[98:101], v[142:145], v[208:211], v[98:101]
	v_mfma_f32_16x16x32_bf16 v[98:101], v[146:149], v[212:215], v[98:101]
	v_mfma_f32_16x16x32_bf16 v[94:97], v[158:161], v[212:215], v[94:97]
	v_mfma_f32_16x16x32_bf16 v[94:97], v[154:157], v[208:211], v[94:97]
	v_mfma_f32_16x16x32_bf16 v[78:81], v[154:157], v[216:219], v[78:81]
	v_mfma_f32_16x16x32_bf16 v[78:81], v[158:161], v[220:223], v[78:81]
	v_mfma_f32_16x16x32_bf16 v[82:85], v[146:149], v[220:223], v[82:85]
	v_mfma_f32_16x16x32_bf16 v[82:85], v[142:145], v[216:219], v[82:85]
	v_mfma_f32_16x16x32_bf16 v[74:77], v[162:165], v[216:219], v[74:77]
	v_mfma_f32_16x16x32_bf16 v[74:77], v[166:169], v[220:223], v[74:77]
	v_mfma_f32_16x16x32_bf16 v[70:73], v[174:177], v[220:223], v[70:73]
	v_mfma_f32_16x16x32_bf16 v[70:73], v[170:173], v[216:219], v[70:73]
	v_mfma_f32_16x16x32_bf16 v[86:89], v[170:173], v[208:211], v[86:89]
	v_mfma_f32_16x16x32_bf16 v[86:89], v[174:177], v[212:215], v[86:89]
	v_mfma_f32_16x16x32_bf16 v[90:93], v[166:169], v[212:215], v[90:93]
	v_mfma_f32_16x16x32_bf16 v[90:93], v[162:165], v[208:211], v[90:93]
	v_mfma_f32_16x16x32_bf16 v[106:109], v[162:165], v[200:203], v[106:109]
	v_mfma_f32_16x16x32_bf16 v[106:109], v[166:169], v[204:207], v[106:109]
	v_mfma_f32_16x16x32_bf16 v[102:105], v[174:177], v[204:207], v[102:105]
	v_mfma_f32_16x16x32_bf16 v[102:105], v[170:173], v[200:203], v[102:105]
	v_mfma_f32_16x16x32_bf16 v[118:121], v[170:173], v[178:181], v[118:121]
	v_mfma_f32_16x16x32_bf16 v[118:121], v[174:177], v[196:199], v[118:121]
	v_mfma_f32_16x16x32_bf16 v[122:125], v[166:169], v[196:199], v[122:125]
	v_mfma_f32_16x16x32_bf16 v[122:125], v[162:165], v[178:181], v[122:125]
	s_setprio 0
	s_barrier
; #define PG8_STAGE(bufoff, gbase, voff) do { _Pragma("unroll") for (int _i = 0; _i < 2; ++_i) \
;         __builtin_amdgcn_global_load_lds((const unsigned*)((const char*)(gbase) + (voff)[_i]), (PG8_LAS unsigned*)(lds + (bufoff) + ldsw + _i * 8192), 16, 0, 0); } while (0)
; #define PG8_LDA(dst, b, h) do { _Pragma("unroll") for (int m = 0; m < 4; ++m) _Pragma("unroll") for (int k = 0; k < 2; ++k) dst[m][k] = *(const PG8_LAS bf16x8*)(lds + PG8_SA(b, h) + aoff + m * 2048 + k * 1024); } while (0)
; #define PG8_MMA(ai, bj, At, Bt) do { __builtin_amdgcn_s_setprio(1); _Pragma("unroll") for (int m = 0; m < 4; ++m) _Pragma("unroll") for (int n = 0; n < 2; ++n) _Pragma("unroll") for (int k = 0; k < 2; ++k) \
;         acc[ai][bj][m][n] = __builtin_amdgcn_mfma_f32_16x16x32_bf16(Bt[n][k], At[m][k], acc[ai][bj][m][n], 0, 0, 0); __builtin_amdgcn_s_setprio(0); } while (0)
; #define PG8_WAIT_V(n) asm volatile("s_waitcnt vmcnt(" #n ")" ::: "memory")
; #define PG8_WAIT_L(n) asm volatile("s_waitcnt lgkmcnt(" #n ")" ::: "memory")
; #define PG8_BAR __builtin_amdgcn_s_barrier()
; #define PG8_SCHED __builtin_amdgcn_sched_barrier(0)
;     ...
;         for (int t = 0; t < nt; t += 2) {
;             const bool last = (t == nt - 2);
;             const char* a1 = cA + (size_t)(t + 1) * kstep;
;             const char* a2 = last ? nA : cA + (size_t)(t + 2) * kstep; const char* b2 = last ? nB : cB + (size_t)(t + 2) * kstep;
;     ...
;             PG8_LDA(At, 1, 1); PG8_STAGE(PG8_SB(1, 0), b3, voffB); PG8_STAGE(PG8_SB(1, 1), b3 + hstep, voffB); PG8_STAGE(PG8_SA(1, 0), a3, voffA);
;             PG8_WAIT_V(8); PG8_WAIT_L(0); PG8_BAR; PG8_MMA(1, 0, At, B0); PG8_MMA(1, 1, At, B1); PG8_BAR; PG8_SCHED;
	s_add_i32 s18, s42, s30
	v_lshl_add_u64 v[182:183], v[182:183], 0, s[64:65]
	s_mov_b32 m0, s18
	ds_read_b128 v[178:181], v152 offset:49152
	ds_read_b128 v[196:199], v152 offset:50176
	ds_read_b128 v[200:203], v152 offset:51200
	ds_read_b128 v[204:207], v152 offset:52224
	ds_read_b128 v[208:211], v152 offset:53248
	ds_read_b128 v[212:215], v152 offset:54272
	ds_read_b128 v[216:219], v152 offset:55296
	ds_read_b128 v[220:223], v152 offset:56320
	global_load_lds_dwordx4 v[182:183], off
	s_add_i32 m0, s18, 0x2000
	s_add_u32 s18, s24, 0x20080
	v_lshl_add_u64 v[182:183], v[186:187], 0, s[64:65]
	s_addc_u32 s19, s25, 0
	s_add_i32 s24, s43, s30
	global_load_lds_dwordx4 v[182:183], off
	s_mov_b32 m0, s24
	s_nop 0
	global_load_lds_dwordx4 v32, s[18:19]
	s_add_i32 m0, s24, 0x2000
	s_nop 0
	global_load_lds_dwordx4 v136, s[18:19]
	v_lshl_add_u64 v[182:183], v[188:189], 0, s[64:65]
	s_mov_b32 m0, s40
	s_nop 0
	global_load_lds_dwordx4 v[182:183], off
	v_lshl_add_u64 v[182:183], v[190:191], 0, s[64:65]
	s_mov_b32 m0, s41
	s_nop 0
	global_load_lds_dwordx4 v[182:183], off
	s_waitcnt vmcnt(8)
	s_waitcnt lgkmcnt(0)
	s_barrier
	s_setprio 1
	s_waitcnt lgkmcnt(0)
	v_mfma_f32_16x16x32_bf16 v[66:69], v[142:145], v[178:181], v[66:69]
	v_mfma_f32_16x16x32_bf16 v[66:69], v[146:149], v[196:199], v[66:69]
	v_mfma_f32_16x16x32_bf16 v[62:65], v[158:161], v[196:199], v[62:65]
	v_mfma_f32_16x16x32_bf16 v[62:65], v[154:157], v[178:181], v[62:65]
	v_mfma_f32_16x16x32_bf16 v[46:49], v[154:157], v[200:203], v[46:49]
	v_mfma_f32_16x16x32_bf16 v[46:49], v[158:161], v[204:207], v[46:49]
	v_mfma_f32_16x16x32_bf16 v[50:53], v[146:149], v[204:207], v[50:53]
	v_mfma_f32_16x16x32_bf16 v[50:53], v[142:145], v[200:203], v[50:53]
	v_mfma_f32_16x16x32_bf16 v[34:37], v[142:145], v[208:211], v[34:37]
	v_mfma_f32_16x16x32_bf16 v[34:37], v[146:149], v[212:215], v[34:37]
	v_mfma_f32_16x16x32_bf16 v[26:29], v[158:161], v[212:215], v[26:29]
	v_mfma_f32_16x16x32_bf16 v[26:29], v[154:157], v[208:211], v[26:29]
	v_mfma_f32_16x16x32_bf16 v[10:13], v[154:157], v[216:219], v[10:13]
	v_mfma_f32_16x16x32_bf16 v[10:13], v[158:161], v[220:223], v[10:13]
	v_mfma_f32_16x16x32_bf16 v[14:17], v[146:149], v[220:223], v[14:17]
	v_mfma_f32_16x16x32_bf16 v[14:17], v[142:145], v[216:219], v[14:17]
	v_mfma_f32_16x16x32_bf16 v[6:9], v[162:165], v[216:219], v[6:9]
	v_mfma_f32_16x16x32_bf16 v[6:9], v[166:169], v[220:223], v[6:9]
	v_mfma_f32_16x16x32_bf16 v[2:5], v[174:177], v[220:223], v[2:5]
	v_mfma_f32_16x16x32_bf16 v[2:5], v[170:173], v[216:219], v[2:5]
	v_mfma_f32_16x16x32_bf16 v[18:21], v[170:173], v[208:211], v[18:21]
	v_mfma_f32_16x16x32_bf16 v[18:21], v[174:177], v[212:215], v[18:21]
	v_mfma_f32_16x16x32_bf16 v[22:25], v[166:169], v[212:215], v[22:25]
	v_mfma_f32_16x16x32_bf16 v[22:25], v[162:165], v[208:211], v[22:25]
	v_mfma_f32_16x16x32_bf16 v[42:45], v[162:165], v[200:203], v[42:45]
	v_mfma_f32_16x16x32_bf16 v[42:45], v[166:169], v[204:207], v[42:45]
	v_mfma_f32_16x16x32_bf16 v[38:41], v[174:177], v[204:207], v[38:41]
	v_mfma_f32_16x16x32_bf16 v[38:41], v[170:173], v[200:203], v[38:41]
	v_mfma_f32_16x16x32_bf16 v[54:57], v[170:173], v[178:181], v[54:57]
	v_mfma_f32_16x16x32_bf16 v[54:57], v[174:177], v[196:199], v[54:57]
	v_mfma_f32_16x16x32_bf16 v[58:61], v[166:169], v[196:199], v[58:61]
	v_mfma_f32_16x16x32_bf16 v[58:61], v[162:165], v[178:181], v[58:61]
	s_setprio 0
	s_barrier
	s_add_i32 s78, s78, 2
	s_add_u32 s48, s48, 0x100
	s_addc_u32 s74, s74, 0
	s_cmp_gt_u32 s78, 5
	s_mov_b64 s[18:19], s[4:5]
	s_cbranch_scc0 .LBB0_748
	s_and_b64 vcc, exec, s[8:9]
	s_cbranch_vccz .LBB0_751
	s_barrier

; #define PG8_STAGE(bufoff, gbase, voff) do { _Pragma("unroll") for (int _i = 0; _i < 2; ++_i) \
;         __builtin_amdgcn_global_load_lds((const unsigned*)((const char*)(gbase) + (voff)[_i]), (PG8_LAS unsigned*)(lds + (bufoff) + ldsw + _i * 8192), 16, 0, 0); } while (0)
; #define PG8_LDA(dst, b, h) do { _Pragma("unroll") for (int m = 0; m < 4; ++m) _Pragma("unroll") for (int k = 0; k < 2; ++k) dst[m][k] = *(const PG8_LAS bf16x8*)(lds + PG8_SA(b, h) + aoff + m * 2048 + k * 1024); } while (0)
; #define PG8_LDB(dst, b, h) do { _Pragma("unroll") for (int n = 0; n < 2; ++n) _Pragma("unroll") for (int k = 0; k < 2; ++k) dst[n][k] = *(const PG8_LAS bf16x8*)(lds + PG8_SB(b, h) + boff + n * 2048 + k * 1024); } while (0)
; #define PG8_MMA(ai, bj, At, Bt) do { __builtin_amdgcn_s_setprio(1); _Pragma("unroll") for (int m = 0; m < 4; ++m) _Pragma("unroll") for (int n = 0; n < 2; ++n) _Pragma("unroll") for (int k = 0; k < 2; ++k) \
;         acc[ai][bj][m][n] = __builtin_amdgcn_mfma_f32_16x16x32_bf16(Bt[n][k], At[m][k], acc[ai][bj][m][n], 0, 0, 0); __builtin_amdgcn_s_setprio(0); } while (0)
; #define PG8_WAIT_V(n) asm volatile("s_waitcnt vmcnt(" #n ")" ::: "memory")
; #define PG8_WAIT_L(n) asm volatile("s_waitcnt lgkmcnt(" #n ")" ::: "memory")
; #define PG8_BAR __builtin_amdgcn_s_barrier()
; #define PG8_SCHED __builtin_amdgcn_sched_barrier(0)
;     ...
;         for (int t = 0; t < nt; t += 2) {
;             const bool last = (t == nt - 2);
;             const char* a1 = cA + (size_t)(t + 1) * kstep;
;             const char* a2 = last ? nA : cA + (size_t)(t + 2) * kstep; const char* b2 = last ? nB : cB + (size_t)(t + 2) * kstep;
;             const char* a3 = a2 + kstep; const char* b3 = b2 + kstep;
;             if (last && has_next) S.a_ready(nxt);
;             if constexpr (SP2) {
;             PG8_LDB(B0, 0, 0); PG8_LDB(B1, 0, 1); PG8_SCHED; PG8_LDA(At, 0, 0); PG8_STAGE(PG8_SA(1, 1), a1 + hstepA, voffA);
;             PG8_WAIT_V(8); PG8_WAIT_L(0); PG8_BAR; PG8_MMA(0, 0, At, B0); PG8_MMA(0, 1, At, B1); PG8_BAR; PG8_SCHED;
;             PG8_LDA(At, 0, 1); PG8_STAGE(PG8_SB(0, 0), b2, voffB); PG8_STAGE(PG8_SB(0, 1), b2 + hstep, voffB); PG8_STAGE(PG8_SA(0, 0), a2, voffA);
;             PG8_WAIT_V(8); PG8_WAIT_L(0); PG8_BAR; PG8_MMA(1, 0, At, B0); PG8_MMA(1, 1, At, B1); PG8_BAR; PG8_SCHED;
.LBB0_766:
	s_add_u32 s29, s24, s28
	s_addc_u32 s42, s25, 0
	s_add_u32 s30, s29, 0x100
	s_addc_u32 s31, s42, 0
	s_and_b64 s[6:7], s[26:27], exec
	s_cselect_b32 s31, s15, s31
	s_cselect_b32 s30, s14, s30
	s_add_u32 s6, s22, s28
	s_addc_u32 s7, s23, 0
	s_add_u32 s28, s6, 0x100
	s_addc_u32 s38, s7, 0
	s_add_i32 s46, 0, 0x10000
	s_and_b64 s[6:7], s[26:27], exec
	s_cselect_b32 s39, s13, s38
	s_cselect_b32 s38, s33, s28
	s_add_i32 s7, 0, 0x14000
	s_add_u32 s92, s29, 0xf0080
	s_addc_u32 s93, s42, 0
	s_add_i32 s42, s46, s53
	s_add_i32 m0, s19, 0xc000
	s_add_i32 s47, s19, 0xe000
	s_add_i32 s6, s42, 0x2000
	v_add_u32_e32 v149, s46, v146
	s_add_u32 s90, s38, 0x10000
	ds_read_b128 v[138:141], v149
	ds_read_b128 v[142:145], v149 offset:1024
	ds_read_b128 v[150:153], v149 offset:2048
	ds_read_b128 v[154:157], v149 offset:3072
	v_add_u32_e32 v149, s7, v146
	s_addc_u32 s91, s39, 0
	s_add_i32 s43, s7, s53
	ds_read_b128 v[158:161], v149
	ds_read_b128 v[162:165], v149 offset:1024
	ds_read_b128 v[166:169], v149 offset:2048
	ds_read_b128 v[170:173], v149 offset:3072
	s_add_i32 s75, s43, 0x2000
	s_add_i32 vcc_hi, 0, 0x18000
	s_add_i32 s49, 0, 0x1c000
	s_add_u32 s28, s30, 0xf0000
	s_addc_u32 s29, s31, 0
	s_add_i32 vcc_lo, vcc_hi, s53
	s_add_i32 s51, vcc_lo, 0x2000
	s_add_u32 s26, s38, 0x10080
	s_addc_u32 s27, s39, 0
	s_add_i32 s7, s49, s53
	s_add_i32 s46, s7, 0x2000
	ds_read_b128 v[174:177], v148
	ds_read_b128 v[178:181], v148 offset:1024
	ds_read_b128 v[196:199], v148 offset:2048
	ds_read_b128 v[200:203], v148 offset:3072
	ds_read_b128 v[204:207], v148 offset:4096
	ds_read_b128 v[208:211], v148 offset:5120
	ds_read_b128 v[212:215], v148 offset:6144
	ds_read_b128 v[216:219], v148 offset:7168
	global_load_lds_dwordx4 v136, s[92:93]
	s_mov_b32 m0, s47
	s_nop 0
	global_load_lds_dwordx4 v134, s[92:93]
	s_waitcnt vmcnt(8)
	s_waitcnt lgkmcnt(0)
	s_barrier
	s_setprio 1
	s_waitcnt lgkmcnt(0)
	v_mfma_f32_16x16x32_bf16 v[130:133], v[138:141], v[174:177], v[130:133]
	v_mfma_f32_16x16x32_bf16 v[130:133], v[142:145], v[178:181], v[130:133]
	v_mfma_f32_16x16x32_bf16 v[126:129], v[154:157], v[178:181], v[126:129]
	v_mfma_f32_16x16x32_bf16 v[126:129], v[150:153], v[174:177], v[126:129]
	v_mfma_f32_16x16x32_bf16 v[110:113], v[150:153], v[196:199], v[110:113]
	v_mfma_f32_16x16x32_bf16 v[110:113], v[154:157], v[200:203], v[110:113]
	v_mfma_f32_16x16x32_bf16 v[114:117], v[142:145], v[200:203], v[114:117]
	v_mfma_f32_16x16x32_bf16 v[114:117], v[138:141], v[196:199], v[114:117]
	v_mfma_f32_16x16x32_bf16 v[98:101], v[138:141], v[204:207], v[98:101]
	v_mfma_f32_16x16x32_bf16 v[98:101], v[142:145], v[208:211], v[98:101]
	v_mfma_f32_16x16x32_bf16 v[94:97], v[154:157], v[208:211], v[94:97]
	v_mfma_f32_16x16x32_bf16 v[94:97], v[150:153], v[204:207], v[94:97]
	v_mfma_f32_16x16x32_bf16 v[78:81], v[150:153], v[212:215], v[78:81]
	v_mfma_f32_16x16x32_bf16 v[78:81], v[154:157], v[216:219], v[78:81]
	v_mfma_f32_16x16x32_bf16 v[82:85], v[142:145], v[216:219], v[82:85]
	v_mfma_f32_16x16x32_bf16 v[82:85], v[138:141], v[212:215], v[82:85]
	v_mfma_f32_16x16x32_bf16 v[74:77], v[158:161], v[212:215], v[74:77]
	v_mfma_f32_16x16x32_bf16 v[74:77], v[162:165], v[216:219], v[74:77]
	v_mfma_f32_16x16x32_bf16 v[70:73], v[170:173], v[216:219], v[70:73]
	v_mfma_f32_16x16x32_bf16 v[70:73], v[166:169], v[212:215], v[70:73]
	v_mfma_f32_16x16x32_bf16 v[86:89], v[166:169], v[204:207], v[86:89]
	v_mfma_f32_16x16x32_bf16 v[86:89], v[170:173], v[208:211], v[86:89]
	v_mfma_f32_16x16x32_bf16 v[90:93], v[162:165], v[208:211], v[90:93]
	v_mfma_f32_16x16x32_bf16 v[90:93], v[158:161], v[204:207], v[90:93]
	v_mfma_f32_16x16x32_bf16 v[106:109], v[158:161], v[196:199], v[106:109]
	v_mfma_f32_16x16x32_bf16 v[106:109], v[162:165], v[200:203], v[106:109]
	v_mfma_f32_16x16x32_bf16 v[102:105], v[170:173], v[200:203], v[102:105]
	v_mfma_f32_16x16x32_bf16 v[102:105], v[166:169], v[196:199], v[102:105]
	v_mfma_f32_16x16x32_bf16 v[118:121], v[166:169], v[174:177], v[118:121]
	v_mfma_f32_16x16x32_bf16 v[118:121], v[170:173], v[178:181], v[118:121]
	v_mfma_f32_16x16x32_bf16 v[122:125], v[162:165], v[178:181], v[122:125]
	v_mfma_f32_16x16x32_bf16 v[122:125], v[158:161], v[174:177], v[122:125]
	s_setprio 0
	s_barrier
	s_mov_b32 m0, s42
	v_lshl_add_u64 v[182:183], s[38:39], 0, v[32:33]
	ds_read_b128 v[174:177], v148 offset:16384
	ds_read_b128 v[178:181], v148 offset:17408
	ds_read_b128 v[196:199], v148 offset:18432
	ds_read_b128 v[200:203], v148 offset:19456
	ds_read_b128 v[204:207], v148 offset:20480
	ds_read_b128 v[208:211], v148 offset:21504
	ds_read_b128 v[212:215], v148 offset:22528
	ds_read_b128 v[216:219], v148 offset:23552
	global_load_lds_dwordx4 v[182:183], off
	v_lshl_add_u64 v[186:187], s[38:39], 0, v[30:31]
	s_mov_b32 m0, s6
	s_nop 0
	global_load_lds_dwordx4 v[186:187], off
	s_mov_b32 m0, s43
	v_lshl_add_u64 v[190:191], s[30:31], 0, v[134:135]
	global_load_lds_dwordx4 v32, s[90:91]
	s_mov_b32 m0, s75
	s_nop 0
	global_load_lds_dwordx4 v30, s[90:91]
	v_lshl_add_u64 v[188:189], s[30:31], 0, v[136:137]
	s_mov_b32 m0, s19
	s_nop 0
	global_load_lds_dwordx4 v[188:189], off
	s_mov_b32 m0, s74
	s_nop 0
	global_load_lds_dwordx4 v[190:191], off
	s_waitcnt vmcnt(8)
	s_waitcnt lgkmcnt(0)
	s_barrier
; #define PG8_STAGE(bufoff, gbase, voff) do { _Pragma("unroll") for (int _i = 0; _i < 2; ++_i) \
;         __builtin_amdgcn_global_load_lds((const unsigned*)((const char*)(gbase) + (voff)[_i]), (PG8_LAS unsigned*)(lds + (bufoff) + ldsw + _i * 8192), 16, 0, 0); } while (0)
; #define PG8_LDA(dst, b, h) do { _Pragma("unroll") for (int m = 0; m < 4; ++m) _Pragma("unroll") for (int k = 0; k < 2; ++k) dst[m][k] = *(const PG8_LAS bf16x8*)(lds + PG8_SA(b, h) + aoff + m * 2048 + k * 1024); } while (0)
; #define PG8_LDB(dst, b, h) do { _Pragma("unroll") for (int n = 0; n < 2; ++n) _Pragma("unroll") for (int k = 0; k < 2; ++k) dst[n][k] = *(const PG8_LAS bf16x8*)(lds + PG8_SB(b, h) + boff + n * 2048 + k * 1024); } while (0)
; #define PG8_MMA(ai, bj, At, Bt) do { __builtin_amdgcn_s_setprio(1); _Pragma("unroll") for (int m = 0; m < 4; ++m) _Pragma("unroll") for (int n = 0; n < 2; ++n) _Pragma("unroll") for (int k = 0; k < 2; ++k) \
;         acc[ai][bj][m][n] = __builtin_amdgcn_mfma_f32_16x16x32_bf16(Bt[n][k], At[m][k], acc[ai][bj][m][n], 0, 0, 0); __builtin_amdgcn_s_setprio(0); } while (0)
; #define PG8_WAIT_V(n) asm volatile("s_waitcnt vmcnt(" #n ")" ::: "memory")
; #define PG8_WAIT_L(n) asm volatile("s_waitcnt lgkmcnt(" #n ")" ::: "memory")
; #define PG8_BAR __builtin_amdgcn_s_barrier()
; #define PG8_SCHED __builtin_amdgcn_sched_barrier(0)
;     ...
;             PG8_WAIT_V(8); PG8_WAIT_L(0); PG8_BAR; PG8_MMA(0, 0, At, B0); PG8_MMA(0, 1, At, B1); PG8_BAR; PG8_SCHED;
;             PG8_LDA(At, 0, 1); PG8_STAGE(PG8_SB(0, 0), b2, voffB); PG8_STAGE(PG8_SB(0, 1), b2 + hstep, voffB); PG8_STAGE(PG8_SA(0, 0), a2, voffA);
;             PG8_WAIT_V(8); PG8_WAIT_L(0); PG8_BAR; PG8_MMA(1, 0, At, B0); PG8_MMA(1, 1, At, B1); PG8_BAR; PG8_SCHED;
;             PG8_LDB(B0, 1, 0); PG8_LDB(B1, 1, 1); PG8_SCHED; PG8_LDA(At, 1, 0); PG8_STAGE(PG8_SA(0, 1), a2 + hstepA, voffA);
;             PG8_WAIT_V(8); PG8_WAIT_L(0); PG8_BAR; PG8_MMA(0, 0, At, B0); PG8_MMA(0, 1, At, B1); PG8_BAR; PG8_SCHED;
	s_setprio 1
	s_waitcnt lgkmcnt(0)
	v_mfma_f32_16x16x32_bf16 v[66:69], v[138:141], v[174:177], v[66:69]
	v_mfma_f32_16x16x32_bf16 v[66:69], v[142:145], v[178:181], v[66:69]
	v_mfma_f32_16x16x32_bf16 v[62:65], v[154:157], v[178:181], v[62:65]
	v_mfma_f32_16x16x32_bf16 v[62:65], v[150:153], v[174:177], v[62:65]
	v_mfma_f32_16x16x32_bf16 v[46:49], v[150:153], v[196:199], v[46:49]
	v_mfma_f32_16x16x32_bf16 v[46:49], v[154:157], v[200:203], v[46:49]
	v_mfma_f32_16x16x32_bf16 v[50:53], v[142:145], v[200:203], v[50:53]
	v_mfma_f32_16x16x32_bf16 v[50:53], v[138:141], v[196:199], v[50:53]
	v_mfma_f32_16x16x32_bf16 v[34:37], v[138:141], v[204:207], v[34:37]
	v_mfma_f32_16x16x32_bf16 v[34:37], v[142:145], v[208:211], v[34:37]
	v_mfma_f32_16x16x32_bf16 v[26:29], v[154:157], v[208:211], v[26:29]
	v_mfma_f32_16x16x32_bf16 v[26:29], v[150:153], v[204:207], v[26:29]
	v_mfma_f32_16x16x32_bf16 v[10:13], v[150:153], v[212:215], v[10:13]
	v_mfma_f32_16x16x32_bf16 v[10:13], v[154:157], v[216:219], v[10:13]
	v_mfma_f32_16x16x32_bf16 v[14:17], v[142:145], v[216:219], v[14:17]
	v_mfma_f32_16x16x32_bf16 v[14:17], v[138:141], v[212:215], v[14:17]
	v_mfma_f32_16x16x32_bf16 v[6:9], v[158:161], v[212:215], v[6:9]
	v_mfma_f32_16x16x32_bf16 v[6:9], v[162:165], v[216:219], v[6:9]
	v_mfma_f32_16x16x32_bf16 v[2:5], v[170:173], v[216:219], v[2:5]
	v_mfma_f32_16x16x32_bf16 v[2:5], v[166:169], v[212:215], v[2:5]
	v_mfma_f32_16x16x32_bf16 v[18:21], v[166:169], v[204:207], v[18:21]
	v_mfma_f32_16x16x32_bf16 v[18:21], v[170:173], v[208:211], v[18:21]
	v_mfma_f32_16x16x32_bf16 v[22:25], v[162:165], v[208:211], v[22:25]
	v_mfma_f32_16x16x32_bf16 v[22:25], v[158:161], v[204:207], v[22:25]
	v_mfma_f32_16x16x32_bf16 v[42:45], v[158:161], v[196:199], v[42:45]
	v_mfma_f32_16x16x32_bf16 v[42:45], v[162:165], v[200:203], v[42:45]
	v_mfma_f32_16x16x32_bf16 v[38:41], v[170:173], v[200:203], v[38:41]
	v_mfma_f32_16x16x32_bf16 v[38:41], v[166:169], v[196:199], v[38:41]
	v_mfma_f32_16x16x32_bf16 v[54:57], v[166:169], v[174:177], v[54:57]
	v_mfma_f32_16x16x32_bf16 v[54:57], v[170:173], v[178:181], v[54:57]
	v_mfma_f32_16x16x32_bf16 v[58:61], v[162:165], v[178:181], v[58:61]
	v_mfma_f32_16x16x32_bf16 v[58:61], v[158:161], v[174:177], v[58:61]
	s_setprio 0
	s_barrier
	v_add_u32_e32 v149, vcc_hi, v146
	ds_read_b128 v[138:141], v149
	ds_read_b128 v[142:145], v149 offset:1024
	ds_read_b128 v[150:153], v149 offset:2048
	ds_read_b128 v[154:157], v149 offset:3072
	v_add_u32_e32 v149, s49, v146
	ds_read_b128 v[158:161], v149
	ds_read_b128 v[162:165], v149 offset:1024
	ds_read_b128 v[166:169], v149 offset:2048
	ds_read_b128 v[170:173], v149 offset:3072
	s_mov_b32 m0, s78
	ds_read_b128 v[174:177], v148 offset:32768
	ds_read_b128 v[178:181], v148 offset:33792
	ds_read_b128 v[196:199], v148 offset:34816
	ds_read_b128 v[200:203], v148 offset:35840
	ds_read_b128 v[204:207], v148 offset:36864
	ds_read_b128 v[208:211], v148 offset:37888
	ds_read_b128 v[212:215], v148 offset:38912
	ds_read_b128 v[216:219], v148 offset:39936
	global_load_lds_dwordx4 v136, s[28:29]
	v_lshl_add_u64 v[220:221], s[28:29], 0, v[134:135]
	s_mov_b32 m0, s79
	s_nop 0
	global_load_lds_dwordx4 v[220:221], off
	s_waitcnt vmcnt(8)
	s_waitcnt lgkmcnt(0)
	s_barrier
	s_setprio 1
	s_waitcnt lgkmcnt(0)
	v_mfma_f32_16x16x32_bf16 v[130:133], v[138:141], v[174:177], v[130:133]
	v_mfma_f32_16x16x32_bf16 v[130:133], v[142:145], v[178:181], v[130:133]
	v_mfma_f32_16x16x32_bf16 v[126:129], v[154:157], v[178:181], v[126:129]
	v_mfma_f32_16x16x32_bf16 v[126:129], v[150:153], v[174:177], v[126:129]
	v_mfma_f32_16x16x32_bf16 v[110:113], v[150:153], v[196:199], v[110:113]
	v_mfma_f32_16x16x32_bf16 v[110:113], v[154:157], v[200:203], v[110:113]
	v_mfma_f32_16x16x32_bf16 v[114:117], v[142:145], v[200:203], v[114:117]
	v_mfma_f32_16x16x32_bf16 v[114:117], v[138:141], v[196:199], v[114:117]
	v_mfma_f32_16x16x32_bf16 v[98:101], v[138:141], v[204:207], v[98:101]
	v_mfma_f32_16x16x32_bf16 v[98:101], v[142:145], v[208:211], v[98:101]
	v_mfma_f32_16x16x32_bf16 v[94:97], v[154:157], v[208:211], v[94:97]
	v_mfma_f32_16x16x32_bf16 v[94:97], v[150:153], v[204:207], v[94:97]
	v_mfma_f32_16x16x32_bf16 v[78:81], v[150:153], v[212:215], v[78:81]
	v_mfma_f32_16x16x32_bf16 v[78:81], v[154:157], v[216:219], v[78:81]
	v_mfma_f32_16x16x32_bf16 v[82:85], v[142:145], v[216:219], v[82:85]
	v_mfma_f32_16x16x32_bf16 v[82:85], v[138:141], v[212:215], v[82:85]
	v_mfma_f32_16x16x32_bf16 v[74:77], v[158:161], v[212:215], v[74:77]
	v_mfma_f32_16x16x32_bf16 v[74:77], v[162:165], v[216:219], v[74:77]
	v_mfma_f32_16x16x32_bf16 v[70:73], v[170:173], v[216:219], v[70:73]
	v_mfma_f32_16x16x32_bf16 v[70:73], v[166:169], v[212:215], v[70:73]
	v_mfma_f32_16x16x32_bf16 v[86:89], v[166:169], v[204:207], v[86:89]
	v_mfma_f32_16x16x32_bf16 v[86:89], v[170:173], v[208:211], v[86:89]
	v_mfma_f32_16x16x32_bf16 v[90:93], v[162:165], v[208:211], v[90:93]
	v_mfma_f32_16x16x32_bf16 v[90:93], v[158:161], v[204:207], v[90:93]
	v_mfma_f32_16x16x32_bf16 v[106:109], v[158:161], v[196:199], v[106:109]
	v_mfma_f32_16x16x32_bf16 v[106:109], v[162:165], v[200:203], v[106:109]
	v_mfma_f32_16x16x32_bf16 v[102:105], v[170:173], v[200:203], v[102:105]
	v_mfma_f32_16x16x32_bf16 v[102:105], v[166:169], v[196:199], v[102:105]
	v_mfma_f32_16x16x32_bf16 v[118:121], v[166:169], v[174:177], v[118:121]
	v_mfma_f32_16x16x32_bf16 v[118:121], v[170:173], v[178:181], v[118:121]
	v_mfma_f32_16x16x32_bf16 v[122:125], v[162:165], v[178:181], v[122:125]
	v_mfma_f32_16x16x32_bf16 v[122:125], v[158:161], v[174:177], v[122:125]
	s_setprio 0
	s_barrier
; #define PG8_STAGE(bufoff, gbase, voff) do { _Pragma("unroll") for (int _i = 0; _i < 2; ++_i) \
;         __builtin_amdgcn_global_load_lds((const unsigned*)((const char*)(gbase) + (voff)[_i]), (PG8_LAS unsigned*)(lds + (bufoff) + ldsw + _i * 8192), 16, 0, 0); } while (0)
; #define PG8_LDA(dst, b, h) do { _Pragma("unroll") for (int m = 0; m < 4; ++m) _Pragma("unroll") for (int k = 0; k < 2; ++k) dst[m][k] = *(const PG8_LAS bf16x8*)(lds + PG8_SA(b, h) + aoff + m * 2048 + k * 1024); } while (0)
; #define PG8_MMA(ai, bj, At, Bt) do { __builtin_amdgcn_s_setprio(1); _Pragma("unroll") for (int m = 0; m < 4; ++m) _Pragma("unroll") for (int n = 0; n < 2; ++n) _Pragma("unroll") for (int k = 0; k < 2; ++k) \
;         acc[ai][bj][m][n] = __builtin_amdgcn_mfma_f32_16x16x32_bf16(Bt[n][k], At[m][k], acc[ai][bj][m][n], 0, 0, 0); __builtin_amdgcn_s_setprio(0); } while (0)
; #define PG8_WAIT_V(n) asm volatile("s_waitcnt vmcnt(" #n ")" ::: "memory")
; #define PG8_WAIT_L(n) asm volatile("s_waitcnt lgkmcnt(" #n ")" ::: "memory")
; #define PG8_BAR __builtin_amdgcn_s_barrier()
; #define PG8_SCHED __builtin_amdgcn_sched_barrier(0)
;     ...
;         for (int t = 0; t < nt; t += 2) {
;     ...
;             PG8_LDA(At, 1, 1); PG8_STAGE(PG8_SB(1, 0), b3, voffB); PG8_STAGE(PG8_SB(1, 1), b3 + hstep, voffB); PG8_STAGE(PG8_SA(1, 0), a3, voffA);
;             PG8_WAIT_V(8); PG8_WAIT_L(0); PG8_BAR; PG8_MMA(1, 0, At, B0); PG8_MMA(1, 1, At, B1); PG8_BAR; PG8_SCHED;
	s_mov_b32 m0, vcc_lo
	v_lshl_add_u64 v[182:183], v[182:183], 0, s[64:65]
	ds_read_b128 v[174:177], v148 offset:49152
	ds_read_b128 v[178:181], v148 offset:50176
	ds_read_b128 v[196:199], v148 offset:51200
	ds_read_b128 v[200:203], v148 offset:52224
	ds_read_b128 v[204:207], v148 offset:53248
	ds_read_b128 v[208:211], v148 offset:54272
	ds_read_b128 v[212:215], v148 offset:55296
	ds_read_b128 v[216:219], v148 offset:56320
	global_load_lds_dwordx4 v[182:183], off
	v_lshl_add_u64 v[182:183], v[186:187], 0, s[64:65]
	s_mov_b32 m0, s51
	s_nop 0
	global_load_lds_dwordx4 v[182:183], off
	s_mov_b32 m0, s7
	s_nop 0
	global_load_lds_dwordx4 v32, s[26:27]
	s_mov_b32 m0, s46
	s_nop 0
	global_load_lds_dwordx4 v30, s[26:27]
	v_lshl_add_u64 v[182:183], v[188:189], 0, s[64:65]
	s_mov_b32 m0, s94
	s_nop 0
	global_load_lds_dwordx4 v[182:183], off
	v_lshl_add_u64 v[182:183], v[190:191], 0, s[64:65]
	s_mov_b32 m0, s95
	s_nop 0
	global_load_lds_dwordx4 v[182:183], off
	s_waitcnt vmcnt(8)
	s_waitcnt lgkmcnt(0)
	s_barrier
	s_setprio 1
	s_waitcnt lgkmcnt(0)
	v_mfma_f32_16x16x32_bf16 v[66:69], v[138:141], v[174:177], v[66:69]
	v_mfma_f32_16x16x32_bf16 v[66:69], v[142:145], v[178:181], v[66:69]
	v_mfma_f32_16x16x32_bf16 v[62:65], v[154:157], v[178:181], v[62:65]
	v_mfma_f32_16x16x32_bf16 v[62:65], v[150:153], v[174:177], v[62:65]
	v_mfma_f32_16x16x32_bf16 v[46:49], v[150:153], v[196:199], v[46:49]
	v_mfma_f32_16x16x32_bf16 v[46:49], v[154:157], v[200:203], v[46:49]
	v_mfma_f32_16x16x32_bf16 v[50:53], v[142:145], v[200:203], v[50:53]
	v_mfma_f32_16x16x32_bf16 v[50:53], v[138:141], v[196:199], v[50:53]
	v_mfma_f32_16x16x32_bf16 v[34:37], v[138:141], v[204:207], v[34:37]
	v_mfma_f32_16x16x32_bf16 v[34:37], v[142:145], v[208:211], v[34:37]
	v_mfma_f32_16x16x32_bf16 v[26:29], v[154:157], v[208:211], v[26:29]
	v_mfma_f32_16x16x32_bf16 v[26:29], v[150:153], v[204:207], v[26:29]
	v_mfma_f32_16x16x32_bf16 v[10:13], v[150:153], v[212:215], v[10:13]
	v_mfma_f32_16x16x32_bf16 v[10:13], v[154:157], v[216:219], v[10:13]
	v_mfma_f32_16x16x32_bf16 v[14:17], v[142:145], v[216:219], v[14:17]
	v_mfma_f32_16x16x32_bf16 v[14:17], v[138:141], v[212:215], v[14:17]
	v_mfma_f32_16x16x32_bf16 v[6:9], v[158:161], v[212:215], v[6:9]
	v_mfma_f32_16x16x32_bf16 v[6:9], v[162:165], v[216:219], v[6:9]
	v_mfma_f32_16x16x32_bf16 v[2:5], v[170:173], v[216:219], v[2:5]
	v_mfma_f32_16x16x32_bf16 v[2:5], v[166:169], v[212:215], v[2:5]
	v_mfma_f32_16x16x32_bf16 v[18:21], v[166:169], v[204:207], v[18:21]
	v_mfma_f32_16x16x32_bf16 v[18:21], v[170:173], v[208:211], v[18:21]
	v_mfma_f32_16x16x32_bf16 v[22:25], v[162:165], v[208:211], v[22:25]
	v_mfma_f32_16x16x32_bf16 v[22:25], v[158:161], v[204:207], v[22:25]
	v_mfma_f32_16x16x32_bf16 v[42:45], v[158:161], v[196:199], v[42:45]
	v_mfma_f32_16x16x32_bf16 v[42:45], v[162:165], v[200:203], v[42:45]
	v_mfma_f32_16x16x32_bf16 v[38:41], v[170:173], v[200:203], v[38:41]
	v_mfma_f32_16x16x32_bf16 v[38:41], v[166:169], v[196:199], v[38:41]
	v_mfma_f32_16x16x32_bf16 v[54:57], v[166:169], v[174:177], v[54:57]
	v_mfma_f32_16x16x32_bf16 v[54:57], v[170:173], v[178:181], v[54:57]
	v_mfma_f32_16x16x32_bf16 v[58:61], v[162:165], v[178:181], v[58:61]
	v_mfma_f32_16x16x32_bf16 v[58:61], v[158:161], v[174:177], v[58:61]
	s_setprio 0
	s_barrier
	s_movk_i32 s28, 0x100
	s_andn2_b64 vcc, exec, s[4:5]
	s_mov_b64 s[26:27], -1
	s_mov_b64 s[4:5], 0
	s_cbranch_vccz .LBB0_766
	s_and_b64 vcc, exec, s[10:11]
	s_cbranch_vccz .LBB0_769
	s_barrier

; #define PG8_STAGE(bufoff, gbase, voff) do { _Pragma("unroll") for (int _i = 0; _i < 2; ++_i) \
;         __builtin_amdgcn_global_load_lds((const unsigned*)((const char*)(gbase) + (voff)[_i]), (PG8_LAS unsigned*)(lds + (bufoff) + ldsw + _i * 8192), 16, 0, 0); } while (0)
; #define PG8_LDA(dst, b, h) do { _Pragma("unroll") for (int m = 0; m < 4; ++m) _Pragma("unroll") for (int k = 0; k < 2; ++k) dst[m][k] = *(const PG8_LAS bf16x8*)(lds + PG8_SA(b, h) + aoff + m * 2048 + k * 1024); } while (0)
; #define PG8_LDB(dst, b, h) do { _Pragma("unroll") for (int n = 0; n < 2; ++n) _Pragma("unroll") for (int k = 0; k < 2; ++k) dst[n][k] = *(const PG8_LAS bf16x8*)(lds + PG8_SB(b, h) + boff + n * 2048 + k * 1024); } while (0)
; #define PG8_MMA(ai, bj, At, Bt) do { __builtin_amdgcn_s_setprio(1); _Pragma("unroll") for (int m = 0; m < 4; ++m) _Pragma("unroll") for (int n = 0; n < 2; ++n) _Pragma("unroll") for (int k = 0; k < 2; ++k) \
;         acc[ai][bj][m][n] = __builtin_amdgcn_mfma_f32_16x16x32_bf16(Bt[n][k], At[m][k], acc[ai][bj][m][n], 0, 0, 0); __builtin_amdgcn_s_setprio(0); } while (0)
; #define PG8_WAIT_V(n) asm volatile("s_waitcnt vmcnt(" #n ")" ::: "memory")
; #define PG8_WAIT_L(n) asm volatile("s_waitcnt lgkmcnt(" #n ")" ::: "memory")
; #define PG8_BAR __builtin_amdgcn_s_barrier()
; #define PG8_SCHED __builtin_amdgcn_sched_barrier(0)
;     ...
;         for (int t = 0; t < nt; t += 2) {
;             const bool last = (t == nt - 2);
;             const char* a1 = cA + (size_t)(t + 1) * kstep;
;             const char* a2 = last ? nA : cA + (size_t)(t + 2) * kstep; const char* b2 = last ? nB : cB + (size_t)(t + 2) * kstep;
;             const char* a3 = a2 + kstep; const char* b3 = b2 + kstep;
;             if (last && has_next) S.a_ready(nxt);
;             if constexpr (SP2) {
;             PG8_LDB(B0, 0, 0); PG8_LDB(B1, 0, 1); PG8_SCHED; PG8_LDA(At, 0, 0); PG8_STAGE(PG8_SA(1, 1), a1 + hstepA, voffA);
;             PG8_WAIT_V(8); PG8_WAIT_L(0); PG8_BAR; PG8_MMA(0, 0, At, B0); PG8_MMA(0, 1, At, B1); PG8_BAR; PG8_SCHED;
;             PG8_LDA(At, 0, 1); PG8_STAGE(PG8_SB(0, 0), b2, voffB); PG8_STAGE(PG8_SB(0, 1), b2 + hstep, voffB); PG8_STAGE(PG8_SA(0, 0), a2, voffA);
;             PG8_WAIT_V(8); PG8_WAIT_L(0); PG8_BAR; PG8_MMA(1, 0, At, B0); PG8_MMA(1, 1, At, B1); PG8_BAR; PG8_SCHED;
.LBB0_1064:
	s_add_u32 s30, s28, 0x100
	s_addc_u32 s31, s29, 0
	s_add_i32 s23, 0, 0x10000
	s_cmp_eq_u32 s40, s19
	s_cselect_b32 s93, s91, s31
	s_cselect_b32 s92, s90, s30
	v_add_u32_e32 v32, s23, v239
	s_cselect_b32 s39, s95, s17
	s_cselect_b32 s38, s94, s9
	s_add_i32 s25, 0, 0x14000
	ds_read_b128 v[72:75], v32
	ds_read_b128 v[76:79], v32 offset:1024
	ds_read_b128 v[80:83], v32 offset:2048
	ds_read_b128 v[88:91], v32 offset:3072
	v_add_u32_e32 v32, s25, v239
	ds_read_b128 v[152:155], v32
	ds_read_b128 v[156:159], v32 offset:1024
	ds_read_b128 v[160:163], v32 offset:2048
	ds_read_b128 v[164:167], v32 offset:3072
	s_add_i32 m0, s56, 0xc000
	ds_read_b128 v[168:171], v251
	ds_read_b128 v[172:175], v251 offset:1024
	ds_read_b128 v[176:179], v251 offset:2048
	ds_read_b128 v[200:203], v251 offset:3072
	ds_read_b128 v[204:207], v251 offset:4096
	ds_read_b128 v[208:211], v251 offset:5120
	ds_read_b128 v[212:215], v251 offset:6144
	ds_read_b128 v[216:219], v251 offset:7168
	global_load_lds_dwordx4 v196, s[28:29]
	s_add_i32 m0, s56, 0xe000
	s_nop 0
	global_load_lds_dwordx4 v198, s[28:29]
	s_waitcnt vmcnt(8)
	s_waitcnt lgkmcnt(0)
	s_barrier
	s_setprio 1
	s_waitcnt lgkmcnt(0)
	v_mfma_f32_16x16x32_bf16 v[84:87], v[72:75], v[168:171], v[84:87]
	v_mfma_f32_16x16x32_bf16 v[84:87], v[76:79], v[172:175], v[84:87]
	v_mfma_f32_16x16x32_bf16 v[148:151], v[88:91], v[172:175], v[148:151]
	v_mfma_f32_16x16x32_bf16 v[148:151], v[80:83], v[168:171], v[148:151]
	v_mfma_f32_16x16x32_bf16 v[132:135], v[80:83], v[176:179], v[132:135]
	v_mfma_f32_16x16x32_bf16 v[132:135], v[88:91], v[200:203], v[132:135]
	v_mfma_f32_16x16x32_bf16 v[136:139], v[76:79], v[200:203], v[136:139]
	v_mfma_f32_16x16x32_bf16 v[136:139], v[72:75], v[176:179], v[136:139]
	v_mfma_f32_16x16x32_bf16 v[120:123], v[72:75], v[204:207], v[120:123]
	v_mfma_f32_16x16x32_bf16 v[120:123], v[76:79], v[208:211], v[120:123]
	v_mfma_f32_16x16x32_bf16 v[116:119], v[88:91], v[208:211], v[116:119]
	v_mfma_f32_16x16x32_bf16 v[116:119], v[80:83], v[204:207], v[116:119]
	v_mfma_f32_16x16x32_bf16 v[100:103], v[80:83], v[212:215], v[100:103]
	v_mfma_f32_16x16x32_bf16 v[100:103], v[88:91], v[216:219], v[100:103]
	v_mfma_f32_16x16x32_bf16 v[104:107], v[76:79], v[216:219], v[104:107]
	v_mfma_f32_16x16x32_bf16 v[104:107], v[72:75], v[212:215], v[104:107]
	v_mfma_f32_16x16x32_bf16 v[96:99], v[152:155], v[212:215], v[96:99]
	v_mfma_f32_16x16x32_bf16 v[96:99], v[156:159], v[216:219], v[96:99]
	v_mfma_f32_16x16x32_bf16 v[92:95], v[164:167], v[216:219], v[92:95]
	v_mfma_f32_16x16x32_bf16 v[92:95], v[160:163], v[212:215], v[92:95]
	v_mfma_f32_16x16x32_bf16 v[108:111], v[160:163], v[204:207], v[108:111]
	v_mfma_f32_16x16x32_bf16 v[108:111], v[164:167], v[208:211], v[108:111]
	v_mfma_f32_16x16x32_bf16 v[112:115], v[156:159], v[208:211], v[112:115]
	v_mfma_f32_16x16x32_bf16 v[112:115], v[152:155], v[204:207], v[112:115]
	v_mfma_f32_16x16x32_bf16 v[128:131], v[152:155], v[176:179], v[128:131]
	v_mfma_f32_16x16x32_bf16 v[128:131], v[156:159], v[200:203], v[128:131]
	v_mfma_f32_16x16x32_bf16 v[124:127], v[164:167], v[200:203], v[124:127]
	v_mfma_f32_16x16x32_bf16 v[124:127], v[160:163], v[176:179], v[124:127]
	v_mfma_f32_16x16x32_bf16 v[140:143], v[160:163], v[168:171], v[140:143]
	v_mfma_f32_16x16x32_bf16 v[140:143], v[164:167], v[172:175], v[140:143]
	v_mfma_f32_16x16x32_bf16 v[144:147], v[156:159], v[172:175], v[144:147]
	v_mfma_f32_16x16x32_bf16 v[144:147], v[152:155], v[168:171], v[144:147]
	s_setprio 0
	s_barrier
	s_add_i32 s23, s23, s3
	v_lshl_add_u64 v[186:187], s[38:39], 0, v[30:31]
	s_mov_b32 m0, s23
	ds_read_b128 v[168:171], v251 offset:16384
	ds_read_b128 v[172:175], v251 offset:17408
	ds_read_b128 v[176:179], v251 offset:18432
	ds_read_b128 v[200:203], v251 offset:19456
	ds_read_b128 v[204:207], v251 offset:20480
	ds_read_b128 v[208:211], v251 offset:21504
	ds_read_b128 v[212:215], v251 offset:22528
	ds_read_b128 v[216:219], v251 offset:23552
	global_load_lds_dwordx4 v[186:187], off
	s_add_i32 m0, s23, 0x2000
	s_add_u32 s28, s38, 0x80000
	v_lshl_add_u64 v[188:189], s[38:39], 0, v[180:181]
	s_addc_u32 s29, s39, 0
	s_add_i32 s23, s25, s3
	global_load_lds_dwordx4 v[188:189], off
	s_mov_b32 m0, s23
	v_lshl_add_u64 v[190:191], s[92:93], 0, v[30:31]
	global_load_lds_dwordx4 v30, s[28:29]
	v_lshl_add_u64 v[34:35], s[28:29], 0, v[180:181]
	s_add_i32 m0, s23, 0x2000
	v_lshl_add_u64 v[220:221], s[92:93], 0, v[180:181]
	global_load_lds_dwordx4 v[34:35], off
	s_mov_b32 m0, s56
	s_nop 0
	global_load_lds_dwordx4 v[190:191], off
	s_mov_b32 m0, s41
	s_nop 0
	global_load_lds_dwordx4 v[220:221], off
	s_waitcnt vmcnt(8)
	s_waitcnt lgkmcnt(0)
	s_barrier
; #define PG8_STAGE(bufoff, gbase, voff) do { _Pragma("unroll") for (int _i = 0; _i < 2; ++_i) \
;         __builtin_amdgcn_global_load_lds((const unsigned*)((const char*)(gbase) + (voff)[_i]), (PG8_LAS unsigned*)(lds + (bufoff) + ldsw + _i * 8192), 16, 0, 0); } while (0)
; #define PG8_LDA(dst, b, h) do { _Pragma("unroll") for (int m = 0; m < 4; ++m) _Pragma("unroll") for (int k = 0; k < 2; ++k) dst[m][k] = *(const PG8_LAS bf16x8*)(lds + PG8_SA(b, h) + aoff + m * 2048 + k * 1024); } while (0)
; #define PG8_LDB(dst, b, h) do { _Pragma("unroll") for (int n = 0; n < 2; ++n) _Pragma("unroll") for (int k = 0; k < 2; ++k) dst[n][k] = *(const PG8_LAS bf16x8*)(lds + PG8_SB(b, h) + boff + n * 2048 + k * 1024); } while (0)
; #define PG8_MMA(ai, bj, At, Bt) do { __builtin_amdgcn_s_setprio(1); _Pragma("unroll") for (int m = 0; m < 4; ++m) _Pragma("unroll") for (int n = 0; n < 2; ++n) _Pragma("unroll") for (int k = 0; k < 2; ++k) \
;         acc[ai][bj][m][n] = __builtin_amdgcn_mfma_f32_16x16x32_bf16(Bt[n][k], At[m][k], acc[ai][bj][m][n], 0, 0, 0); __builtin_amdgcn_s_setprio(0); } while (0)
; #define PG8_WAIT_V(n) asm volatile("s_waitcnt vmcnt(" #n ")" ::: "memory")
; #define PG8_WAIT_L(n) asm volatile("s_waitcnt lgkmcnt(" #n ")" ::: "memory")
; #define PG8_BAR __builtin_amdgcn_s_barrier()
; #define PG8_SCHED __builtin_amdgcn_sched_barrier(0)
;     ...
;             PG8_WAIT_V(8); PG8_WAIT_L(0); PG8_BAR; PG8_MMA(0, 0, At, B0); PG8_MMA(0, 1, At, B1); PG8_BAR; PG8_SCHED;
;             PG8_LDA(At, 0, 1); PG8_STAGE(PG8_SB(0, 0), b2, voffB); PG8_STAGE(PG8_SB(0, 1), b2 + hstep, voffB); PG8_STAGE(PG8_SA(0, 0), a2, voffA);
;             PG8_WAIT_V(8); PG8_WAIT_L(0); PG8_BAR; PG8_MMA(1, 0, At, B0); PG8_MMA(1, 1, At, B1); PG8_BAR; PG8_SCHED;
;             PG8_LDB(B0, 1, 0); PG8_LDB(B1, 1, 1); PG8_SCHED; PG8_LDA(At, 1, 0); PG8_STAGE(PG8_SA(0, 1), a2 + hstepA, voffA);
;             PG8_WAIT_V(8); PG8_WAIT_L(0); PG8_BAR; PG8_MMA(0, 0, At, B0); PG8_MMA(0, 1, At, B1); PG8_BAR; PG8_SCHED;
	s_setprio 1
	s_waitcnt lgkmcnt(0)
	v_mfma_f32_16x16x32_bf16 v[68:71], v[72:75], v[168:171], v[68:71]
	v_mfma_f32_16x16x32_bf16 v[68:71], v[76:79], v[172:175], v[68:71]
	v_mfma_f32_16x16x32_bf16 v[64:67], v[88:91], v[172:175], v[64:67]
	v_mfma_f32_16x16x32_bf16 v[64:67], v[80:83], v[168:171], v[64:67]
	v_mfma_f32_16x16x32_bf16 v[48:51], v[80:83], v[176:179], v[48:51]
	v_mfma_f32_16x16x32_bf16 v[48:51], v[88:91], v[200:203], v[48:51]
	v_mfma_f32_16x16x32_bf16 v[52:55], v[76:79], v[200:203], v[52:55]
	v_mfma_f32_16x16x32_bf16 v[52:55], v[72:75], v[176:179], v[52:55]
	v_mfma_f32_16x16x32_bf16 v[34:37], v[72:75], v[204:207], v[36:39]
	v_mfma_f32_16x16x32_bf16 v[34:37], v[76:79], v[208:211], v[34:37]
	v_mfma_f32_16x16x32_bf16 v[26:29], v[88:91], v[208:211], v[26:29]
	v_mfma_f32_16x16x32_bf16 v[26:29], v[80:83], v[204:207], v[26:29]
	v_mfma_f32_16x16x32_bf16 v[10:13], v[80:83], v[212:215], v[10:13]
	v_mfma_f32_16x16x32_bf16 v[10:13], v[88:91], v[216:219], v[10:13]
	v_mfma_f32_16x16x32_bf16 v[14:17], v[76:79], v[216:219], v[14:17]
	v_mfma_f32_16x16x32_bf16 v[14:17], v[72:75], v[212:215], v[14:17]
	v_mfma_f32_16x16x32_bf16 v[6:9], v[152:155], v[212:215], v[6:9]
	v_mfma_f32_16x16x32_bf16 v[6:9], v[156:159], v[216:219], v[6:9]
	v_mfma_f32_16x16x32_bf16 v[2:5], v[164:167], v[216:219], v[2:5]
	v_mfma_f32_16x16x32_bf16 v[2:5], v[160:163], v[212:215], v[2:5]
	v_mfma_f32_16x16x32_bf16 v[18:21], v[160:163], v[204:207], v[18:21]
	v_mfma_f32_16x16x32_bf16 v[18:21], v[164:167], v[208:211], v[18:21]
	v_mfma_f32_16x16x32_bf16 v[22:25], v[156:159], v[208:211], v[22:25]
	v_mfma_f32_16x16x32_bf16 v[22:25], v[152:155], v[204:207], v[22:25]
	v_mfma_f32_16x16x32_bf16 v[44:47], v[152:155], v[176:179], v[44:47]
	v_mfma_f32_16x16x32_bf16 v[44:47], v[156:159], v[200:203], v[44:47]
	v_mfma_f32_16x16x32_bf16 v[40:43], v[164:167], v[200:203], v[40:43]
	v_mfma_f32_16x16x32_bf16 v[40:43], v[160:163], v[176:179], v[40:43]
	v_mfma_f32_16x16x32_bf16 v[56:59], v[160:163], v[168:171], v[56:59]
	v_mfma_f32_16x16x32_bf16 v[56:59], v[164:167], v[172:175], v[56:59]
	v_mfma_f32_16x16x32_bf16 v[60:63], v[156:159], v[172:175], v[60:63]
	v_mfma_f32_16x16x32_bf16 v[60:63], v[152:155], v[168:171], v[60:63]
	s_setprio 0
	s_barrier
	s_add_i32 s23, 0, 0x18000
	v_add_u32_e32 v32, s23, v239
	s_add_i32 s25, 0, 0x1c000
	ds_read_b128 v[72:75], v32
	ds_read_b128 v[76:79], v32 offset:1024
	ds_read_b128 v[80:83], v32 offset:2048
	ds_read_b128 v[88:91], v32 offset:3072
	v_add_u32_e32 v32, s25, v239
	ds_read_b128 v[152:155], v32
	ds_read_b128 v[156:159], v32 offset:1024
	ds_read_b128 v[160:163], v32 offset:2048
	ds_read_b128 v[164:167], v32 offset:3072
	s_add_u32 s28, s92, 0x80000
	s_addc_u32 s29, s93, 0
	s_mov_b32 m0, s74
	ds_read_b128 v[168:171], v251 offset:32768
	ds_read_b128 v[172:175], v251 offset:33792
	ds_read_b128 v[176:179], v251 offset:34816
	ds_read_b128 v[200:203], v251 offset:35840
	ds_read_b128 v[204:207], v251 offset:36864
	ds_read_b128 v[208:211], v251 offset:37888
	ds_read_b128 v[212:215], v251 offset:38912
	ds_read_b128 v[216:219], v251 offset:39936
	global_load_lds_dwordx4 v30, s[28:29]
	s_mov_b32 m0, s96
	s_nop 0
	global_load_lds_dwordx4 v180, s[28:29]
	s_waitcnt vmcnt(8)
	s_waitcnt lgkmcnt(0)
	s_barrier
	s_setprio 1
	s_waitcnt lgkmcnt(0)
	v_mfma_f32_16x16x32_bf16 v[84:87], v[72:75], v[168:171], v[84:87]
	v_mfma_f32_16x16x32_bf16 v[84:87], v[76:79], v[172:175], v[84:87]
	v_mfma_f32_16x16x32_bf16 v[148:151], v[88:91], v[172:175], v[148:151]
	v_mfma_f32_16x16x32_bf16 v[148:151], v[80:83], v[168:171], v[148:151]
	v_mfma_f32_16x16x32_bf16 v[132:135], v[80:83], v[176:179], v[132:135]
	v_mfma_f32_16x16x32_bf16 v[132:135], v[88:91], v[200:203], v[132:135]
	v_mfma_f32_16x16x32_bf16 v[136:139], v[76:79], v[200:203], v[136:139]
	v_mfma_f32_16x16x32_bf16 v[136:139], v[72:75], v[176:179], v[136:139]
	v_mfma_f32_16x16x32_bf16 v[120:123], v[72:75], v[204:207], v[120:123]
	v_mfma_f32_16x16x32_bf16 v[120:123], v[76:79], v[208:211], v[120:123]
	v_mfma_f32_16x16x32_bf16 v[116:119], v[88:91], v[208:211], v[116:119]
	v_mfma_f32_16x16x32_bf16 v[116:119], v[80:83], v[204:207], v[116:119]
	v_mfma_f32_16x16x32_bf16 v[100:103], v[80:83], v[212:215], v[100:103]
	v_mfma_f32_16x16x32_bf16 v[100:103], v[88:91], v[216:219], v[100:103]
	v_mfma_f32_16x16x32_bf16 v[104:107], v[76:79], v[216:219], v[104:107]
	v_mfma_f32_16x16x32_bf16 v[104:107], v[72:75], v[212:215], v[104:107]
	v_mfma_f32_16x16x32_bf16 v[96:99], v[152:155], v[212:215], v[96:99]
	v_mfma_f32_16x16x32_bf16 v[96:99], v[156:159], v[216:219], v[96:99]
	v_mfma_f32_16x16x32_bf16 v[92:95], v[164:167], v[216:219], v[92:95]
	v_mfma_f32_16x16x32_bf16 v[92:95], v[160:163], v[212:215], v[92:95]
	v_mfma_f32_16x16x32_bf16 v[108:111], v[160:163], v[204:207], v[108:111]
	v_mfma_f32_16x16x32_bf16 v[108:111], v[164:167], v[208:211], v[108:111]
	v_mfma_f32_16x16x32_bf16 v[112:115], v[156:159], v[208:211], v[112:115]
	v_mfma_f32_16x16x32_bf16 v[112:115], v[152:155], v[204:207], v[112:115]
	v_mfma_f32_16x16x32_bf16 v[128:131], v[152:155], v[176:179], v[128:131]
	v_mfma_f32_16x16x32_bf16 v[128:131], v[156:159], v[200:203], v[128:131]
	v_mfma_f32_16x16x32_bf16 v[124:127], v[164:167], v[200:203], v[124:127]
	v_mfma_f32_16x16x32_bf16 v[124:127], v[160:163], v[176:179], v[124:127]
	v_mfma_f32_16x16x32_bf16 v[140:143], v[160:163], v[168:171], v[140:143]
	v_mfma_f32_16x16x32_bf16 v[140:143], v[164:167], v[172:175], v[140:143]
	v_mfma_f32_16x16x32_bf16 v[144:147], v[156:159], v[172:175], v[144:147]
	v_mfma_f32_16x16x32_bf16 v[144:147], v[152:155], v[168:171], v[144:147]
	s_setprio 0
	s_barrier
; #define PG8_STAGE(bufoff, gbase, voff) do { _Pragma("unroll") for (int _i = 0; _i < 2; ++_i) \
;         __builtin_amdgcn_global_load_lds((const unsigned*)((const char*)(gbase) + (voff)[_i]), (PG8_LAS unsigned*)(lds + (bufoff) + ldsw + _i * 8192), 16, 0, 0); } while (0)
; #define PG8_LDA(dst, b, h) do { _Pragma("unroll") for (int m = 0; m < 4; ++m) _Pragma("unroll") for (int k = 0; k < 2; ++k) dst[m][k] = *(const PG8_LAS bf16x8*)(lds + PG8_SA(b, h) + aoff + m * 2048 + k * 1024); } while (0)
; #define PG8_MMA(ai, bj, At, Bt) do { __builtin_amdgcn_s_setprio(1); _Pragma("unroll") for (int m = 0; m < 4; ++m) _Pragma("unroll") for (int n = 0; n < 2; ++n) _Pragma("unroll") for (int k = 0; k < 2; ++k) \
;         acc[ai][bj][m][n] = __builtin_amdgcn_mfma_f32_16x16x32_bf16(Bt[n][k], At[m][k], acc[ai][bj][m][n], 0, 0, 0); __builtin_amdgcn_s_setprio(0); } while (0)
; #define PG8_WAIT_V(n) asm volatile("s_waitcnt vmcnt(" #n ")" ::: "memory")
; #define PG8_WAIT_L(n) asm volatile("s_waitcnt lgkmcnt(" #n ")" ::: "memory")
; #define PG8_BAR __builtin_amdgcn_s_barrier()
; #define PG8_SCHED __builtin_amdgcn_sched_barrier(0)
;     ...
;         for (int t = 0; t < nt; t += 2) {
;     ...
;             PG8_LDA(At, 1, 1); PG8_STAGE(PG8_SB(1, 0), b3, voffB); PG8_STAGE(PG8_SB(1, 1), b3 + hstep, voffB); PG8_STAGE(PG8_SA(1, 0), a3, voffA);
;             PG8_WAIT_V(8); PG8_WAIT_L(0); PG8_BAR; PG8_MMA(1, 0, At, B0); PG8_MMA(1, 1, At, B1); PG8_BAR; PG8_SCHED;
	s_add_i32 s23, s23, s3
	v_lshl_add_u64 v[38:39], v[186:187], 0, s[64:65]
	s_mov_b32 m0, s23
	ds_read_b128 v[168:171], v251 offset:49152
	ds_read_b128 v[172:175], v251 offset:50176
	ds_read_b128 v[176:179], v251 offset:51200
	ds_read_b128 v[200:203], v251 offset:52224
	ds_read_b128 v[204:207], v251 offset:53248
	ds_read_b128 v[208:211], v251 offset:54272
	ds_read_b128 v[212:215], v251 offset:55296
	ds_read_b128 v[216:219], v251 offset:56320
	global_load_lds_dwordx4 v[38:39], off
	s_add_i32 m0, s23, 0x2000
	s_add_u32 s28, s38, 0x80080
	v_lshl_add_u64 v[38:39], v[188:189], 0, s[64:65]
	s_addc_u32 s29, s39, 0
	s_add_i32 s23, s25, s3
	global_load_lds_dwordx4 v[38:39], off
	s_mov_b32 m0, s23
	s_nop 0
	global_load_lds_dwordx4 v30, s[28:29]
	s_add_i32 m0, s23, 0x2000
	s_nop 0
	global_load_lds_dwordx4 v180, s[28:29]
	v_lshl_add_u64 v[38:39], v[190:191], 0, s[64:65]
	s_mov_b32 m0, s53
	s_nop 0
	global_load_lds_dwordx4 v[38:39], off
	v_lshl_add_u64 v[38:39], v[220:221], 0, s[64:65]
	s_mov_b32 m0, s4
	s_nop 0
	global_load_lds_dwordx4 v[38:39], off
	s_waitcnt vmcnt(8)
	s_waitcnt lgkmcnt(0)
	s_barrier
	s_setprio 1
	s_waitcnt lgkmcnt(0)
	v_mfma_f32_16x16x32_bf16 v[68:71], v[72:75], v[168:171], v[68:71]
	v_mfma_f32_16x16x32_bf16 v[68:71], v[76:79], v[172:175], v[68:71]
	v_mfma_f32_16x16x32_bf16 v[64:67], v[88:91], v[172:175], v[64:67]
	v_mfma_f32_16x16x32_bf16 v[64:67], v[80:83], v[168:171], v[64:67]
	v_mfma_f32_16x16x32_bf16 v[48:51], v[80:83], v[176:179], v[48:51]
	v_mfma_f32_16x16x32_bf16 v[48:51], v[88:91], v[200:203], v[48:51]
	v_mfma_f32_16x16x32_bf16 v[52:55], v[76:79], v[200:203], v[52:55]
	v_mfma_f32_16x16x32_bf16 v[52:55], v[72:75], v[176:179], v[52:55]
	v_mfma_f32_16x16x32_bf16 v[34:37], v[72:75], v[204:207], v[34:37]
	v_mfma_f32_16x16x32_bf16 v[36:39], v[76:79], v[208:211], v[34:37]
	v_mfma_f32_16x16x32_bf16 v[26:29], v[88:91], v[208:211], v[26:29]
	v_mfma_f32_16x16x32_bf16 v[26:29], v[80:83], v[204:207], v[26:29]
	v_mfma_f32_16x16x32_bf16 v[10:13], v[80:83], v[212:215], v[10:13]
	v_mfma_f32_16x16x32_bf16 v[10:13], v[88:91], v[216:219], v[10:13]
	v_mfma_f32_16x16x32_bf16 v[14:17], v[76:79], v[216:219], v[14:17]
	v_mfma_f32_16x16x32_bf16 v[14:17], v[72:75], v[212:215], v[14:17]
	v_mfma_f32_16x16x32_bf16 v[6:9], v[152:155], v[212:215], v[6:9]
	v_mfma_f32_16x16x32_bf16 v[6:9], v[156:159], v[216:219], v[6:9]
	v_mfma_f32_16x16x32_bf16 v[2:5], v[164:167], v[216:219], v[2:5]
	v_mfma_f32_16x16x32_bf16 v[2:5], v[160:163], v[212:215], v[2:5]
	v_mfma_f32_16x16x32_bf16 v[18:21], v[160:163], v[204:207], v[18:21]
	v_mfma_f32_16x16x32_bf16 v[18:21], v[164:167], v[208:211], v[18:21]
	v_mfma_f32_16x16x32_bf16 v[22:25], v[156:159], v[208:211], v[22:25]
	v_mfma_f32_16x16x32_bf16 v[22:25], v[152:155], v[204:207], v[22:25]
	v_mfma_f32_16x16x32_bf16 v[44:47], v[152:155], v[176:179], v[44:47]
	v_mfma_f32_16x16x32_bf16 v[44:47], v[156:159], v[200:203], v[44:47]
	v_mfma_f32_16x16x32_bf16 v[40:43], v[164:167], v[200:203], v[40:43]
	v_mfma_f32_16x16x32_bf16 v[40:43], v[160:163], v[176:179], v[40:43]
	v_mfma_f32_16x16x32_bf16 v[56:59], v[160:163], v[168:171], v[56:59]
	v_mfma_f32_16x16x32_bf16 v[56:59], v[164:167], v[172:175], v[56:59]
	v_mfma_f32_16x16x32_bf16 v[60:63], v[156:159], v[172:175], v[60:63]
	v_mfma_f32_16x16x32_bf16 v[60:63], v[152:155], v[168:171], v[60:63]
	s_setprio 0
	s_barrier
	s_add_i32 s23, s19, 2
	s_add_u32 s9, s9, 0x100
	s_addc_u32 s17, s17, 0
	s_cmp_ge_i32 s19, s40
	s_mov_b64 s[28:29], s[30:31]
	s_mov_b32 s19, s23
	s_cbranch_scc0 .LBB0_1064
	s_and_b64 vcc, exec, s[14:15]
	s_cbranch_vccz .LBB0_1067
	s_barrier

; #define PG8_STAGE(bufoff, gbase, voff) do { _Pragma("unroll") for (int _i = 0; _i < 2; ++_i) \
;         __builtin_amdgcn_global_load_lds((const unsigned*)((const char*)(gbase) + (voff)[_i]), (PG8_LAS unsigned*)(lds + (bufoff) + ldsw + _i * 8192), 16, 0, 0); } while (0)
; #define PG8_LDA(dst, b, h) do { _Pragma("unroll") for (int m = 0; m < 4; ++m) _Pragma("unroll") for (int k = 0; k < 2; ++k) dst[m][k] = *(const PG8_LAS bf16x8*)(lds + PG8_SA(b, h) + aoff + m * 2048 + k * 1024); } while (0)
; #define PG8_LDB(dst, b, h) do { _Pragma("unroll") for (int n = 0; n < 2; ++n) _Pragma("unroll") for (int k = 0; k < 2; ++k) dst[n][k] = *(const PG8_LAS bf16x8*)(lds + PG8_SB(b, h) + boff + n * 2048 + k * 1024); } while (0)
; #define PG8_MMA(ai, bj, At, Bt) do { __builtin_amdgcn_s_setprio(1); _Pragma("unroll") for (int m = 0; m < 4; ++m) _Pragma("unroll") for (int n = 0; n < 2; ++n) _Pragma("unroll") for (int k = 0; k < 2; ++k) \
;         acc[ai][bj][m][n] = __builtin_amdgcn_mfma_f32_16x16x32_bf16(Bt[n][k], At[m][k], acc[ai][bj][m][n], 0, 0, 0); __builtin_amdgcn_s_setprio(0); } while (0)
; #define PG8_WAIT_V(n) asm volatile("s_waitcnt vmcnt(" #n ")" ::: "memory")
; #define PG8_WAIT_L(n) asm volatile("s_waitcnt lgkmcnt(" #n ")" ::: "memory")
; #define PG8_BAR __builtin_amdgcn_s_barrier()
; #define PG8_SCHED __builtin_amdgcn_sched_barrier(0)
;     ...
;         for (int t = 0; t < nt; t += 2) {
;             const bool last = (t == nt - 2);
;             const char* a1 = cA + (size_t)(t + 1) * kstep;
;             const char* a2 = last ? nA : cA + (size_t)(t + 2) * kstep; const char* b2 = last ? nB : cB + (size_t)(t + 2) * kstep;
;             const char* a3 = a2 + kstep; const char* b3 = b2 + kstep;
;             if (last && has_next) S.a_ready(nxt);
;             if constexpr (SP2) {
;             PG8_LDB(B0, 0, 0); PG8_LDB(B1, 0, 1); PG8_SCHED; PG8_LDA(At, 0, 0); PG8_STAGE(PG8_SA(1, 1), a1 + hstepA, voffA);
;             PG8_WAIT_V(8); PG8_WAIT_L(0); PG8_BAR; PG8_MMA(0, 0, At, B0); PG8_MMA(0, 1, At, B1); PG8_BAR; PG8_SCHED;
;             PG8_LDA(At, 0, 1); PG8_STAGE(PG8_SB(0, 0), b2, voffB); PG8_STAGE(PG8_SB(0, 1), b2 + hstep, voffB); PG8_STAGE(PG8_SA(0, 0), a2, voffA);
;             PG8_WAIT_V(8); PG8_WAIT_L(0); PG8_BAR; PG8_MMA(1, 0, At, B0); PG8_MMA(1, 1, At, B1); PG8_BAR; PG8_SCHED;
.LBB0_1332:
	s_add_u32 s26, s24, 0xfff80080
	s_addc_u32 s27, s25, -1
	s_add_i32 s42, 0, 0x10000
	s_cmp_eq_u32 s79, 28
	s_cselect_b32 s29, s11, s27
	s_cselect_b32 s28, s48, s26
	s_cselect_b32 s27, s9, s78
	s_cselect_b32 s26, s33, s74
	s_add_i32 s46, 0, 0x14000
	v_add_u32_e32 v106, s42, v31
	v_add_u32_e32 v174, s46, v31
	ds_read_b128 v[94:97], v106
	ds_read_b128 v[98:101], v106 offset:1024
	ds_read_b128 v[102:105], v106 offset:2048
	ds_read_b128 v[106:109], v106 offset:3072
	ds_read_b128 v[160:163], v174
	ds_read_b128 v[164:167], v174 offset:1024
	ds_read_b128 v[170:173], v174 offset:2048
	ds_read_b128 v[174:177], v174 offset:3072
	s_add_i32 m0, s19, 0xc000
	ds_read_b128 v[178:181], v169
	ds_read_b128 v[186:189], v169 offset:1024
	ds_read_b128 v[196:199], v169 offset:2048
	ds_read_b128 v[200:203], v169 offset:3072
	ds_read_b128 v[204:207], v169 offset:4096
	ds_read_b128 v[208:211], v169 offset:5120
	ds_read_b128 v[212:215], v169 offset:6144
	ds_read_b128 v[216:219], v169 offset:7168
	global_load_lds_dwordx4 v156, s[24:25]
	s_add_i32 m0, s19, 0xe000
	s_nop 0
	global_load_lds_dwordx4 v158, s[24:25]
	s_waitcnt vmcnt(8)
	s_waitcnt lgkmcnt(0)
	s_barrier
	s_setprio 1
	s_waitcnt lgkmcnt(0)
	v_mfma_f32_16x16x32_bf16 v[146:149], v[94:97], v[178:181], v[146:149]
	v_mfma_f32_16x16x32_bf16 v[146:149], v[98:101], v[186:189], v[146:149]
	v_mfma_f32_16x16x32_bf16 v[142:145], v[106:109], v[186:189], v[142:145]
	v_mfma_f32_16x16x32_bf16 v[142:145], v[102:105], v[178:181], v[142:145]
	v_mfma_f32_16x16x32_bf16 v[126:129], v[102:105], v[196:199], v[126:129]
	v_mfma_f32_16x16x32_bf16 v[126:129], v[106:109], v[200:203], v[126:129]
	v_mfma_f32_16x16x32_bf16 v[130:133], v[98:101], v[200:203], v[130:133]
	v_mfma_f32_16x16x32_bf16 v[130:133], v[94:97], v[196:199], v[130:133]
	v_mfma_f32_16x16x32_bf16 v[114:117], v[94:97], v[204:207], v[114:117]
	v_mfma_f32_16x16x32_bf16 v[114:117], v[98:101], v[208:211], v[114:117]
	v_mfma_f32_16x16x32_bf16 v[110:113], v[106:109], v[208:211], v[110:113]
	v_mfma_f32_16x16x32_bf16 v[110:113], v[102:105], v[204:207], v[110:113]
	v_mfma_f32_16x16x32_bf16 v[78:81], v[102:105], v[212:215], v[78:81]
	v_mfma_f32_16x16x32_bf16 v[78:81], v[106:109], v[216:219], v[78:81]
	v_mfma_f32_16x16x32_bf16 v[82:85], v[98:101], v[216:219], v[82:85]
	v_mfma_f32_16x16x32_bf16 v[82:85], v[94:97], v[212:215], v[82:85]
	v_mfma_f32_16x16x32_bf16 v[74:77], v[160:163], v[212:215], v[74:77]
	v_mfma_f32_16x16x32_bf16 v[74:77], v[164:167], v[216:219], v[74:77]
	v_mfma_f32_16x16x32_bf16 v[70:73], v[174:177], v[216:219], v[70:73]
	v_mfma_f32_16x16x32_bf16 v[70:73], v[170:173], v[212:215], v[70:73]
	v_mfma_f32_16x16x32_bf16 v[86:89], v[170:173], v[204:207], v[86:89]
	v_mfma_f32_16x16x32_bf16 v[86:89], v[174:177], v[208:211], v[86:89]
	v_mfma_f32_16x16x32_bf16 v[90:93], v[164:167], v[208:211], v[90:93]
	v_mfma_f32_16x16x32_bf16 v[90:93], v[160:163], v[204:207], v[90:93]
	v_mfma_f32_16x16x32_bf16 v[122:125], v[160:163], v[196:199], v[122:125]
	v_mfma_f32_16x16x32_bf16 v[122:125], v[164:167], v[200:203], v[122:125]
	v_mfma_f32_16x16x32_bf16 v[118:121], v[174:177], v[200:203], v[118:121]
	v_mfma_f32_16x16x32_bf16 v[118:121], v[170:173], v[196:199], v[118:121]
	v_mfma_f32_16x16x32_bf16 v[134:137], v[170:173], v[178:181], v[134:137]
	v_mfma_f32_16x16x32_bf16 v[134:137], v[174:177], v[186:189], v[134:137]
	v_mfma_f32_16x16x32_bf16 v[138:141], v[164:167], v[186:189], v[138:141]
	v_mfma_f32_16x16x32_bf16 v[138:141], v[160:163], v[178:181], v[138:141]
	s_setprio 0
	s_barrier
	s_add_i32 s42, s42, s30
	v_lshl_add_u64 v[182:183], s[26:27], 0, v[32:33]
	s_mov_b32 m0, s42
	ds_read_b128 v[178:181], v169 offset:16384
	ds_read_b128 v[186:189], v169 offset:17408
	ds_read_b128 v[196:199], v169 offset:18432
	ds_read_b128 v[200:203], v169 offset:19456
	ds_read_b128 v[204:207], v169 offset:20480
	ds_read_b128 v[208:211], v169 offset:21504
	ds_read_b128 v[212:215], v169 offset:22528
	ds_read_b128 v[216:219], v169 offset:23552
	global_load_lds_dwordx4 v[182:183], off
	s_add_i32 m0, s42, 0x2000
	s_add_u32 s42, s26, 0x80000
	v_lshl_add_u64 v[190:191], s[26:27], 0, v[154:155]
	s_addc_u32 s43, s27, 0
	s_add_i32 s46, s46, s30
	global_load_lds_dwordx4 v[190:191], off
	s_mov_b32 m0, s46
	v_lshl_add_u64 v[222:223], s[28:29], 0, v[152:153]
	global_load_lds_dwordx4 v32, s[42:43]
	s_add_i32 m0, s46, 0x2000
	s_nop 0
	global_load_lds_dwordx4 v154, s[42:43]
	v_lshl_add_u64 v[220:221], s[28:29], 0, v[150:151]
	s_mov_b32 m0, s19
	s_nop 0
	global_load_lds_dwordx4 v[220:221], off
	s_mov_b32 m0, s23
	s_nop 0
	global_load_lds_dwordx4 v[222:223], off
	s_waitcnt vmcnt(8)
	s_waitcnt lgkmcnt(0)
	s_barrier
; #define PG8_STAGE(bufoff, gbase, voff) do { _Pragma("unroll") for (int _i = 0; _i < 2; ++_i) \
;         __builtin_amdgcn_global_load_lds((const unsigned*)((const char*)(gbase) + (voff)[_i]), (PG8_LAS unsigned*)(lds + (bufoff) + ldsw + _i * 8192), 16, 0, 0); } while (0)
; #define PG8_LDA(dst, b, h) do { _Pragma("unroll") for (int m = 0; m < 4; ++m) _Pragma("unroll") for (int k = 0; k < 2; ++k) dst[m][k] = *(const PG8_LAS bf16x8*)(lds + PG8_SA(b, h) + aoff + m * 2048 + k * 1024); } while (0)
; #define PG8_LDB(dst, b, h) do { _Pragma("unroll") for (int n = 0; n < 2; ++n) _Pragma("unroll") for (int k = 0; k < 2; ++k) dst[n][k] = *(const PG8_LAS bf16x8*)(lds + PG8_SB(b, h) + boff + n * 2048 + k * 1024); } while (0)
; #define PG8_MMA(ai, bj, At, Bt) do { __builtin_amdgcn_s_setprio(1); _Pragma("unroll") for (int m = 0; m < 4; ++m) _Pragma("unroll") for (int n = 0; n < 2; ++n) _Pragma("unroll") for (int k = 0; k < 2; ++k) \
;         acc[ai][bj][m][n] = __builtin_amdgcn_mfma_f32_16x16x32_bf16(Bt[n][k], At[m][k], acc[ai][bj][m][n], 0, 0, 0); __builtin_amdgcn_s_setprio(0); } while (0)
; #define PG8_WAIT_V(n) asm volatile("s_waitcnt vmcnt(" #n ")" ::: "memory")
; #define PG8_WAIT_L(n) asm volatile("s_waitcnt lgkmcnt(" #n ")" ::: "memory")
; #define PG8_BAR __builtin_amdgcn_s_barrier()
; #define PG8_SCHED __builtin_amdgcn_sched_barrier(0)
;     ...
;             PG8_WAIT_V(8); PG8_WAIT_L(0); PG8_BAR; PG8_MMA(0, 0, At, B0); PG8_MMA(0, 1, At, B1); PG8_BAR; PG8_SCHED;
;             PG8_LDA(At, 0, 1); PG8_STAGE(PG8_SB(0, 0), b2, voffB); PG8_STAGE(PG8_SB(0, 1), b2 + hstep, voffB); PG8_STAGE(PG8_SA(0, 0), a2, voffA);
;             PG8_WAIT_V(8); PG8_WAIT_L(0); PG8_BAR; PG8_MMA(1, 0, At, B0); PG8_MMA(1, 1, At, B1); PG8_BAR; PG8_SCHED;
;             PG8_LDB(B0, 1, 0); PG8_LDB(B1, 1, 1); PG8_SCHED; PG8_LDA(At, 1, 0); PG8_STAGE(PG8_SA(0, 1), a2 + hstepA, voffA);
;             PG8_WAIT_V(8); PG8_WAIT_L(0); PG8_BAR; PG8_MMA(0, 0, At, B0); PG8_MMA(0, 1, At, B1); PG8_BAR; PG8_SCHED;
	s_setprio 1
	s_waitcnt lgkmcnt(0)
	v_mfma_f32_16x16x32_bf16 v[66:69], v[94:97], v[178:181], v[66:69]
	v_mfma_f32_16x16x32_bf16 v[66:69], v[98:101], v[186:189], v[66:69]
	v_mfma_f32_16x16x32_bf16 v[62:65], v[106:109], v[186:189], v[62:65]
	v_mfma_f32_16x16x32_bf16 v[62:65], v[102:105], v[178:181], v[62:65]
	v_mfma_f32_16x16x32_bf16 v[46:49], v[102:105], v[196:199], v[46:49]
	v_mfma_f32_16x16x32_bf16 v[46:49], v[106:109], v[200:203], v[46:49]
	v_mfma_f32_16x16x32_bf16 v[50:53], v[98:101], v[200:203], v[50:53]
	v_mfma_f32_16x16x32_bf16 v[50:53], v[94:97], v[196:199], v[50:53]
	v_mfma_f32_16x16x32_bf16 v[34:37], v[94:97], v[204:207], v[34:37]
	v_mfma_f32_16x16x32_bf16 v[34:37], v[98:101], v[208:211], v[34:37]
	v_mfma_f32_16x16x32_bf16 v[26:29], v[106:109], v[208:211], v[26:29]
	v_mfma_f32_16x16x32_bf16 v[26:29], v[102:105], v[204:207], v[26:29]
	v_mfma_f32_16x16x32_bf16 v[10:13], v[102:105], v[212:215], v[10:13]
	v_mfma_f32_16x16x32_bf16 v[10:13], v[106:109], v[216:219], v[10:13]
	v_mfma_f32_16x16x32_bf16 v[14:17], v[98:101], v[216:219], v[14:17]
	v_mfma_f32_16x16x32_bf16 v[14:17], v[94:97], v[212:215], v[14:17]
	v_mfma_f32_16x16x32_bf16 v[6:9], v[160:163], v[212:215], v[6:9]
	v_mfma_f32_16x16x32_bf16 v[6:9], v[164:167], v[216:219], v[6:9]
	v_mfma_f32_16x16x32_bf16 v[2:5], v[174:177], v[216:219], v[2:5]
	v_mfma_f32_16x16x32_bf16 v[2:5], v[170:173], v[212:215], v[2:5]
	v_mfma_f32_16x16x32_bf16 v[18:21], v[170:173], v[204:207], v[18:21]
	v_mfma_f32_16x16x32_bf16 v[18:21], v[174:177], v[208:211], v[18:21]
	v_mfma_f32_16x16x32_bf16 v[22:25], v[164:167], v[208:211], v[22:25]
	v_mfma_f32_16x16x32_bf16 v[22:25], v[160:163], v[204:207], v[22:25]
	v_mfma_f32_16x16x32_bf16 v[42:45], v[160:163], v[196:199], v[42:45]
	v_mfma_f32_16x16x32_bf16 v[42:45], v[164:167], v[200:203], v[42:45]
	v_mfma_f32_16x16x32_bf16 v[38:41], v[174:177], v[200:203], v[38:41]
	v_mfma_f32_16x16x32_bf16 v[38:41], v[170:173], v[196:199], v[38:41]
	v_mfma_f32_16x16x32_bf16 v[54:57], v[170:173], v[178:181], v[54:57]
	v_mfma_f32_16x16x32_bf16 v[54:57], v[174:177], v[186:189], v[54:57]
	v_mfma_f32_16x16x32_bf16 v[58:61], v[164:167], v[186:189], v[58:61]
	v_mfma_f32_16x16x32_bf16 v[58:61], v[160:163], v[178:181], v[58:61]
	s_setprio 0
	s_barrier
	s_add_i32 s42, 0, 0x18000
	s_add_i32 s43, 0, 0x1c000
	v_add_u32_e32 v106, s42, v31
	v_add_u32_e32 v174, s43, v31
	ds_read_b128 v[94:97], v106
	ds_read_b128 v[98:101], v106 offset:1024
	ds_read_b128 v[102:105], v106 offset:2048
	ds_read_b128 v[106:109], v106 offset:3072
	ds_read_b128 v[160:163], v174
	ds_read_b128 v[164:167], v174 offset:1024
	ds_read_b128 v[170:173], v174 offset:2048
	ds_read_b128 v[174:177], v174 offset:3072
	s_add_u32 s28, s28, 0x80000
	s_addc_u32 s29, s29, 0
	s_mov_b32 m0, s31
	ds_read_b128 v[178:181], v169 offset:32768
	ds_read_b128 v[186:189], v169 offset:33792
	ds_read_b128 v[196:199], v169 offset:34816
	ds_read_b128 v[200:203], v169 offset:35840
	ds_read_b128 v[204:207], v169 offset:36864
	ds_read_b128 v[208:211], v169 offset:37888
	ds_read_b128 v[212:215], v169 offset:38912
	ds_read_b128 v[216:219], v169 offset:39936
	global_load_lds_dwordx4 v150, s[28:29]
	v_lshl_add_u64 v[224:225], s[28:29], 0, v[152:153]
	s_mov_b32 m0, s38
	s_nop 0
	global_load_lds_dwordx4 v[224:225], off
	s_waitcnt vmcnt(8)
	s_waitcnt lgkmcnt(0)
	s_barrier
	s_setprio 1
	s_waitcnt lgkmcnt(0)
	v_mfma_f32_16x16x32_bf16 v[146:149], v[94:97], v[178:181], v[146:149]
	v_mfma_f32_16x16x32_bf16 v[146:149], v[98:101], v[186:189], v[146:149]
	v_mfma_f32_16x16x32_bf16 v[142:145], v[106:109], v[186:189], v[142:145]
	v_mfma_f32_16x16x32_bf16 v[142:145], v[102:105], v[178:181], v[142:145]
	v_mfma_f32_16x16x32_bf16 v[126:129], v[102:105], v[196:199], v[126:129]
	v_mfma_f32_16x16x32_bf16 v[126:129], v[106:109], v[200:203], v[126:129]
	v_mfma_f32_16x16x32_bf16 v[130:133], v[98:101], v[200:203], v[130:133]
	v_mfma_f32_16x16x32_bf16 v[130:133], v[94:97], v[196:199], v[130:133]
	v_mfma_f32_16x16x32_bf16 v[114:117], v[94:97], v[204:207], v[114:117]
	v_mfma_f32_16x16x32_bf16 v[114:117], v[98:101], v[208:211], v[114:117]
	v_mfma_f32_16x16x32_bf16 v[110:113], v[106:109], v[208:211], v[110:113]
	v_mfma_f32_16x16x32_bf16 v[110:113], v[102:105], v[204:207], v[110:113]
	v_mfma_f32_16x16x32_bf16 v[78:81], v[102:105], v[212:215], v[78:81]
	v_mfma_f32_16x16x32_bf16 v[78:81], v[106:109], v[216:219], v[78:81]
	v_mfma_f32_16x16x32_bf16 v[82:85], v[98:101], v[216:219], v[82:85]
	v_mfma_f32_16x16x32_bf16 v[82:85], v[94:97], v[212:215], v[82:85]
	v_mfma_f32_16x16x32_bf16 v[74:77], v[160:163], v[212:215], v[74:77]
	v_mfma_f32_16x16x32_bf16 v[74:77], v[164:167], v[216:219], v[74:77]
	v_mfma_f32_16x16x32_bf16 v[70:73], v[174:177], v[216:219], v[70:73]
	v_mfma_f32_16x16x32_bf16 v[70:73], v[170:173], v[212:215], v[70:73]
	v_mfma_f32_16x16x32_bf16 v[86:89], v[170:173], v[204:207], v[86:89]
	v_mfma_f32_16x16x32_bf16 v[86:89], v[174:177], v[208:211], v[86:89]
	v_mfma_f32_16x16x32_bf16 v[90:93], v[164:167], v[208:211], v[90:93]
	v_mfma_f32_16x16x32_bf16 v[90:93], v[160:163], v[204:207], v[90:93]
	v_mfma_f32_16x16x32_bf16 v[122:125], v[160:163], v[196:199], v[122:125]
	v_mfma_f32_16x16x32_bf16 v[122:125], v[164:167], v[200:203], v[122:125]
	v_mfma_f32_16x16x32_bf16 v[118:121], v[174:177], v[200:203], v[118:121]
	v_mfma_f32_16x16x32_bf16 v[118:121], v[170:173], v[196:199], v[118:121]
	v_mfma_f32_16x16x32_bf16 v[134:137], v[170:173], v[178:181], v[134:137]
	v_mfma_f32_16x16x32_bf16 v[134:137], v[174:177], v[186:189], v[134:137]
	v_mfma_f32_16x16x32_bf16 v[138:141], v[164:167], v[186:189], v[138:141]
	v_mfma_f32_16x16x32_bf16 v[138:141], v[160:163], v[178:181], v[138:141]
	s_setprio 0
	s_barrier
; #define PG8_STAGE(bufoff, gbase, voff) do { _Pragma("unroll") for (int _i = 0; _i < 2; ++_i) \
;         __builtin_amdgcn_global_load_lds((const unsigned*)((const char*)(gbase) + (voff)[_i]), (PG8_LAS unsigned*)(lds + (bufoff) + ldsw + _i * 8192), 16, 0, 0); } while (0)
; #define PG8_LDA(dst, b, h) do { _Pragma("unroll") for (int m = 0; m < 4; ++m) _Pragma("unroll") for (int k = 0; k < 2; ++k) dst[m][k] = *(const PG8_LAS bf16x8*)(lds + PG8_SA(b, h) + aoff + m * 2048 + k * 1024); } while (0)
; #define PG8_MMA(ai, bj, At, Bt) do { __builtin_amdgcn_s_setprio(1); _Pragma("unroll") for (int m = 0; m < 4; ++m) _Pragma("unroll") for (int n = 0; n < 2; ++n) _Pragma("unroll") for (int k = 0; k < 2; ++k) \
;         acc[ai][bj][m][n] = __builtin_amdgcn_mfma_f32_16x16x32_bf16(Bt[n][k], At[m][k], acc[ai][bj][m][n], 0, 0, 0); __builtin_amdgcn_s_setprio(0); } while (0)
; #define PG8_WAIT_V(n) asm volatile("s_waitcnt vmcnt(" #n ")" ::: "memory")
; #define PG8_WAIT_L(n) asm volatile("s_waitcnt lgkmcnt(" #n ")" ::: "memory")
; #define PG8_BAR __builtin_amdgcn_s_barrier()
; #define PG8_SCHED __builtin_amdgcn_sched_barrier(0)
;     ...
;         for (int t = 0; t < nt; t += 2) {
;     ...
;             PG8_LDA(At, 1, 1); PG8_STAGE(PG8_SB(1, 0), b3, voffB); PG8_STAGE(PG8_SB(1, 1), b3 + hstep, voffB); PG8_STAGE(PG8_SA(1, 0), a3, voffA);
;             PG8_WAIT_V(8); PG8_WAIT_L(0); PG8_BAR; PG8_MMA(1, 0, At, B0); PG8_MMA(1, 1, At, B1); PG8_BAR; PG8_SCHED;
	s_add_i32 s28, s42, s30
	v_lshl_add_u64 v[182:183], v[182:183], 0, s[64:65]
	s_mov_b32 m0, s28
	ds_read_b128 v[178:181], v169 offset:49152
	ds_read_b128 v[186:189], v169 offset:50176
	ds_read_b128 v[196:199], v169 offset:51200
	ds_read_b128 v[200:203], v169 offset:52224
	ds_read_b128 v[204:207], v169 offset:53248
	ds_read_b128 v[208:211], v169 offset:54272
	ds_read_b128 v[212:215], v169 offset:55296
	ds_read_b128 v[216:219], v169 offset:56320
	global_load_lds_dwordx4 v[182:183], off
	s_add_i32 m0, s28, 0x2000
	s_add_u32 s26, s26, 0x80080
	v_lshl_add_u64 v[182:183], v[190:191], 0, s[64:65]
	s_addc_u32 s27, s27, 0
	s_add_i32 s28, s43, s30
	global_load_lds_dwordx4 v[182:183], off
	s_mov_b32 m0, s28
	s_nop 0
	global_load_lds_dwordx4 v32, s[26:27]
	s_add_i32 m0, s28, 0x2000
	s_nop 0
	global_load_lds_dwordx4 v154, s[26:27]
	v_lshl_add_u64 v[182:183], v[220:221], 0, s[64:65]
	s_mov_b32 m0, s41
	s_nop 0
	global_load_lds_dwordx4 v[182:183], off
	v_lshl_add_u64 v[182:183], v[222:223], 0, s[64:65]
	s_mov_b32 m0, s50
	s_nop 0
	global_load_lds_dwordx4 v[182:183], off
	s_waitcnt vmcnt(8)
	s_waitcnt lgkmcnt(0)
	s_barrier
	s_setprio 1
	s_waitcnt lgkmcnt(0)
	v_mfma_f32_16x16x32_bf16 v[66:69], v[94:97], v[178:181], v[66:69]
	v_mfma_f32_16x16x32_bf16 v[66:69], v[98:101], v[186:189], v[66:69]
	v_mfma_f32_16x16x32_bf16 v[62:65], v[106:109], v[186:189], v[62:65]
	v_mfma_f32_16x16x32_bf16 v[62:65], v[102:105], v[178:181], v[62:65]
	v_mfma_f32_16x16x32_bf16 v[46:49], v[102:105], v[196:199], v[46:49]
	v_mfma_f32_16x16x32_bf16 v[46:49], v[106:109], v[200:203], v[46:49]
	v_mfma_f32_16x16x32_bf16 v[50:53], v[98:101], v[200:203], v[50:53]
	v_mfma_f32_16x16x32_bf16 v[50:53], v[94:97], v[196:199], v[50:53]
	v_mfma_f32_16x16x32_bf16 v[34:37], v[94:97], v[204:207], v[34:37]
	v_mfma_f32_16x16x32_bf16 v[34:37], v[98:101], v[208:211], v[34:37]
	v_mfma_f32_16x16x32_bf16 v[26:29], v[106:109], v[208:211], v[26:29]
	v_mfma_f32_16x16x32_bf16 v[26:29], v[102:105], v[204:207], v[26:29]
	v_mfma_f32_16x16x32_bf16 v[10:13], v[102:105], v[212:215], v[10:13]
	v_mfma_f32_16x16x32_bf16 v[10:13], v[106:109], v[216:219], v[10:13]
	v_mfma_f32_16x16x32_bf16 v[14:17], v[98:101], v[216:219], v[14:17]
	v_mfma_f32_16x16x32_bf16 v[14:17], v[94:97], v[212:215], v[14:17]
	v_mfma_f32_16x16x32_bf16 v[6:9], v[160:163], v[212:215], v[6:9]
	v_mfma_f32_16x16x32_bf16 v[6:9], v[164:167], v[216:219], v[6:9]
	v_mfma_f32_16x16x32_bf16 v[2:5], v[174:177], v[216:219], v[2:5]
	v_mfma_f32_16x16x32_bf16 v[2:5], v[170:173], v[212:215], v[2:5]
	v_mfma_f32_16x16x32_bf16 v[18:21], v[170:173], v[204:207], v[18:21]
	v_mfma_f32_16x16x32_bf16 v[18:21], v[174:177], v[208:211], v[18:21]
	v_mfma_f32_16x16x32_bf16 v[22:25], v[164:167], v[208:211], v[22:25]
	v_mfma_f32_16x16x32_bf16 v[22:25], v[160:163], v[204:207], v[22:25]
	v_mfma_f32_16x16x32_bf16 v[42:45], v[160:163], v[196:199], v[42:45]
	v_mfma_f32_16x16x32_bf16 v[42:45], v[164:167], v[200:203], v[42:45]
	v_mfma_f32_16x16x32_bf16 v[38:41], v[174:177], v[200:203], v[38:41]
	v_mfma_f32_16x16x32_bf16 v[38:41], v[170:173], v[196:199], v[38:41]
	v_mfma_f32_16x16x32_bf16 v[54:57], v[170:173], v[178:181], v[54:57]
	v_mfma_f32_16x16x32_bf16 v[54:57], v[174:177], v[186:189], v[54:57]
	v_mfma_f32_16x16x32_bf16 v[58:61], v[164:167], v[186:189], v[58:61]
	v_mfma_f32_16x16x32_bf16 v[58:61], v[160:163], v[178:181], v[58:61]
	s_setprio 0
	s_barrier
	s_add_i32 s79, s79, 2
	s_add_u32 s24, s24, 0x100
	s_addc_u32 s25, s25, 0
	s_add_u32 s74, s74, 0x100
	s_addc_u32 s78, s78, 0
	s_cmp_gt_u32 s79, 29
	s_cbranch_scc0 .LBB0_1332
	s_and_b64 vcc, exec, s[6:7]
	s_cbranch_vccz .LBB0_1335
	s_barrier

; #define PG8_STAGE(bufoff, gbase, voff) do { _Pragma("unroll") for (int _i = 0; _i < 2; ++_i) \
;         __builtin_amdgcn_global_load_lds((const unsigned*)((const char*)(gbase) + (voff)[_i]), (PG8_LAS unsigned*)(lds + (bufoff) + ldsw + _i * 8192), 16, 0, 0); } while (0)
; #define PG8_LDA(dst, b, h) do { _Pragma("unroll") for (int m = 0; m < 4; ++m) _Pragma("unroll") for (int k = 0; k < 2; ++k) dst[m][k] = *(const PG8_LAS bf16x8*)(lds + PG8_SA(b, h) + aoff + m * 2048 + k * 1024); } while (0)
; #define PG8_LDB(dst, b, h) do { _Pragma("unroll") for (int n = 0; n < 2; ++n) _Pragma("unroll") for (int k = 0; k < 2; ++k) dst[n][k] = *(const PG8_LAS bf16x8*)(lds + PG8_SB(b, h) + boff + n * 2048 + k * 1024); } while (0)
; #define PG8_MMA(ai, bj, At, Bt) do { __builtin_amdgcn_s_setprio(1); _Pragma("unroll") for (int m = 0; m < 4; ++m) _Pragma("unroll") for (int n = 0; n < 2; ++n) _Pragma("unroll") for (int k = 0; k < 2; ++k) \
;         acc[ai][bj][m][n] = __builtin_amdgcn_mfma_f32_16x16x32_bf16(Bt[n][k], At[m][k], acc[ai][bj][m][n], 0, 0, 0); __builtin_amdgcn_s_setprio(0); } while (0)
; #define PG8_WAIT_V(n) asm volatile("s_waitcnt vmcnt(" #n ")" ::: "memory")
; #define PG8_WAIT_L(n) asm volatile("s_waitcnt lgkmcnt(" #n ")" ::: "memory")
; #define PG8_BAR __builtin_amdgcn_s_barrier()
; #define PG8_SCHED __builtin_amdgcn_sched_barrier(0)
;     ...
;         for (int t = 0; t < nt; t += 2) {
;             const bool last = (t == nt - 2);
;             const char* a1 = cA + (size_t)(t + 1) * kstep;
;             const char* a2 = last ? nA : cA + (size_t)(t + 2) * kstep; const char* b2 = last ? nB : cB + (size_t)(t + 2) * kstep;
;             const char* a3 = a2 + kstep; const char* b3 = b2 + kstep;
;             if (last && has_next) S.a_ready(nxt);
;             if constexpr (SP2) {
;             PG8_LDB(B0, 0, 0); PG8_LDB(B1, 0, 1); PG8_SCHED; PG8_LDA(At, 0, 0); PG8_STAGE(PG8_SA(1, 1), a1 + hstepA, voffA);
;             PG8_WAIT_V(8); PG8_WAIT_L(0); PG8_BAR; PG8_MMA(0, 0, At, B0); PG8_MMA(0, 1, At, B1); PG8_BAR; PG8_SCHED;
;             PG8_LDA(At, 0, 1); PG8_STAGE(PG8_SB(0, 0), b2, voffB); PG8_STAGE(PG8_SB(0, 1), b2 + hstep, voffB); PG8_STAGE(PG8_SA(0, 0), a2, voffA);
;             PG8_WAIT_V(8); PG8_WAIT_L(0); PG8_BAR; PG8_MMA(1, 0, At, B0); PG8_MMA(1, 1, At, B1); PG8_BAR; PG8_SCHED;
.LBB0_1454:
	s_add_u32 s30, s28, 0x100
	s_addc_u32 s31, s29, 0
	s_add_i32 s27, 0, 0x10000
	s_cmp_eq_u32 s40, s25
	s_cselect_b32 s93, s95, s31
	s_cselect_b32 s92, s94, s30
	v_add_u32_e32 v32, s27, v239
	s_cselect_b32 s39, s97, s23
	s_cselect_b32 s38, s96, s9
	s_add_i32 s33, 0, 0x14000
	ds_read_b128 v[72:75], v32
	ds_read_b128 v[76:79], v32 offset:1024
	ds_read_b128 v[80:83], v32 offset:2048
	ds_read_b128 v[88:91], v32 offset:3072
	v_add_u32_e32 v32, s33, v239
	ds_read_b128 v[152:155], v32
	ds_read_b128 v[156:159], v32 offset:1024
	ds_read_b128 v[160:163], v32 offset:2048
	ds_read_b128 v[164:167], v32 offset:3072
	s_add_i32 m0, s4, 0xc000
	ds_read_b128 v[168:171], v251
	ds_read_b128 v[172:175], v251 offset:1024
	ds_read_b128 v[176:179], v251 offset:2048
	ds_read_b128 v[186:189], v251 offset:3072
	ds_read_b128 v[200:203], v251 offset:4096
	ds_read_b128 v[204:207], v251 offset:5120
	ds_read_b128 v[208:211], v251 offset:6144
	ds_read_b128 v[212:215], v251 offset:7168
	global_load_lds_dwordx4 v196, s[28:29]
	s_add_i32 m0, s4, 0xe000
	s_nop 0
	global_load_lds_dwordx4 v198, s[28:29]
	s_waitcnt vmcnt(8)
	s_waitcnt lgkmcnt(0)
	s_barrier
	s_setprio 1
	s_waitcnt lgkmcnt(0)
	v_mfma_f32_16x16x32_bf16 v[84:87], v[72:75], v[168:171], v[84:87]
	v_mfma_f32_16x16x32_bf16 v[84:87], v[76:79], v[172:175], v[84:87]
	v_mfma_f32_16x16x32_bf16 v[148:151], v[88:91], v[172:175], v[148:151]
	v_mfma_f32_16x16x32_bf16 v[148:151], v[80:83], v[168:171], v[148:151]
	v_mfma_f32_16x16x32_bf16 v[132:135], v[80:83], v[176:179], v[132:135]
	v_mfma_f32_16x16x32_bf16 v[132:135], v[88:91], v[186:189], v[132:135]
	v_mfma_f32_16x16x32_bf16 v[136:139], v[76:79], v[186:189], v[136:139]
	v_mfma_f32_16x16x32_bf16 v[136:139], v[72:75], v[176:179], v[136:139]
	v_mfma_f32_16x16x32_bf16 v[120:123], v[72:75], v[200:203], v[120:123]
	v_mfma_f32_16x16x32_bf16 v[120:123], v[76:79], v[204:207], v[120:123]
	v_mfma_f32_16x16x32_bf16 v[116:119], v[88:91], v[204:207], v[116:119]
	v_mfma_f32_16x16x32_bf16 v[116:119], v[80:83], v[200:203], v[116:119]
	v_mfma_f32_16x16x32_bf16 v[100:103], v[80:83], v[208:211], v[100:103]
	v_mfma_f32_16x16x32_bf16 v[100:103], v[88:91], v[212:215], v[100:103]
	v_mfma_f32_16x16x32_bf16 v[104:107], v[76:79], v[212:215], v[104:107]
	v_mfma_f32_16x16x32_bf16 v[104:107], v[72:75], v[208:211], v[104:107]
	v_mfma_f32_16x16x32_bf16 v[96:99], v[152:155], v[208:211], v[96:99]
	v_mfma_f32_16x16x32_bf16 v[96:99], v[156:159], v[212:215], v[96:99]
	v_mfma_f32_16x16x32_bf16 v[92:95], v[164:167], v[212:215], v[92:95]
	v_mfma_f32_16x16x32_bf16 v[92:95], v[160:163], v[208:211], v[92:95]
	v_mfma_f32_16x16x32_bf16 v[108:111], v[160:163], v[200:203], v[108:111]
	v_mfma_f32_16x16x32_bf16 v[108:111], v[164:167], v[204:207], v[108:111]
	v_mfma_f32_16x16x32_bf16 v[112:115], v[156:159], v[204:207], v[112:115]
	v_mfma_f32_16x16x32_bf16 v[112:115], v[152:155], v[200:203], v[112:115]
	v_mfma_f32_16x16x32_bf16 v[128:131], v[152:155], v[176:179], v[128:131]
	v_mfma_f32_16x16x32_bf16 v[128:131], v[156:159], v[186:189], v[128:131]
	v_mfma_f32_16x16x32_bf16 v[124:127], v[164:167], v[186:189], v[124:127]
	v_mfma_f32_16x16x32_bf16 v[124:127], v[160:163], v[176:179], v[124:127]
	v_mfma_f32_16x16x32_bf16 v[140:143], v[160:163], v[168:171], v[140:143]
	v_mfma_f32_16x16x32_bf16 v[140:143], v[164:167], v[172:175], v[140:143]
	v_mfma_f32_16x16x32_bf16 v[144:147], v[156:159], v[172:175], v[144:147]
	v_mfma_f32_16x16x32_bf16 v[144:147], v[152:155], v[168:171], v[144:147]
	s_setprio 0
	s_barrier
	s_add_i32 s27, s27, s3
	v_lshl_add_u64 v[190:191], s[38:39], 0, v[30:31]
	s_mov_b32 m0, s27
	ds_read_b128 v[168:171], v251 offset:16384
	ds_read_b128 v[172:175], v251 offset:17408
	ds_read_b128 v[176:179], v251 offset:18432
	ds_read_b128 v[186:189], v251 offset:19456
	ds_read_b128 v[200:203], v251 offset:20480
	ds_read_b128 v[204:207], v251 offset:21504
	ds_read_b128 v[208:211], v251 offset:22528
	ds_read_b128 v[212:215], v251 offset:23552
	global_load_lds_dwordx4 v[190:191], off
	s_add_i32 m0, s27, 0x2000
	s_add_u32 s28, s38, 0x200000
	v_lshl_add_u64 v[216:217], s[38:39], 0, v[180:181]
	s_addc_u32 s29, s39, 0
	s_add_i32 s27, s33, s3
	global_load_lds_dwordx4 v[216:217], off
	s_mov_b32 m0, s27
	v_lshl_add_u64 v[218:219], s[92:93], 0, v[30:31]
	global_load_lds_dwordx4 v30, s[28:29]
	v_lshl_add_u64 v[34:35], s[28:29], 0, v[180:181]
	s_add_i32 m0, s27, 0x2000
	v_lshl_add_u64 v[220:221], s[92:93], 0, v[180:181]
	global_load_lds_dwordx4 v[34:35], off
	s_mov_b32 m0, s4
	s_nop 0
	global_load_lds_dwordx4 v[218:219], off
	s_mov_b32 m0, s5
	s_nop 0
	global_load_lds_dwordx4 v[220:221], off
	s_waitcnt vmcnt(8)
	s_waitcnt lgkmcnt(0)
	s_barrier
; #define PG8_STAGE(bufoff, gbase, voff) do { _Pragma("unroll") for (int _i = 0; _i < 2; ++_i) \
;         __builtin_amdgcn_global_load_lds((const unsigned*)((const char*)(gbase) + (voff)[_i]), (PG8_LAS unsigned*)(lds + (bufoff) + ldsw + _i * 8192), 16, 0, 0); } while (0)
; #define PG8_LDA(dst, b, h) do { _Pragma("unroll") for (int m = 0; m < 4; ++m) _Pragma("unroll") for (int k = 0; k < 2; ++k) dst[m][k] = *(const PG8_LAS bf16x8*)(lds + PG8_SA(b, h) + aoff + m * 2048 + k * 1024); } while (0)
; #define PG8_LDB(dst, b, h) do { _Pragma("unroll") for (int n = 0; n < 2; ++n) _Pragma("unroll") for (int k = 0; k < 2; ++k) dst[n][k] = *(const PG8_LAS bf16x8*)(lds + PG8_SB(b, h) + boff + n * 2048 + k * 1024); } while (0)
; #define PG8_MMA(ai, bj, At, Bt) do { __builtin_amdgcn_s_setprio(1); _Pragma("unroll") for (int m = 0; m < 4; ++m) _Pragma("unroll") for (int n = 0; n < 2; ++n) _Pragma("unroll") for (int k = 0; k < 2; ++k) \
;         acc[ai][bj][m][n] = __builtin_amdgcn_mfma_f32_16x16x32_bf16(Bt[n][k], At[m][k], acc[ai][bj][m][n], 0, 0, 0); __builtin_amdgcn_s_setprio(0); } while (0)
; #define PG8_WAIT_V(n) asm volatile("s_waitcnt vmcnt(" #n ")" ::: "memory")
; #define PG8_WAIT_L(n) asm volatile("s_waitcnt lgkmcnt(" #n ")" ::: "memory")
; #define PG8_BAR __builtin_amdgcn_s_barrier()
; #define PG8_SCHED __builtin_amdgcn_sched_barrier(0)
;     ...
;             PG8_WAIT_V(8); PG8_WAIT_L(0); PG8_BAR; PG8_MMA(0, 0, At, B0); PG8_MMA(0, 1, At, B1); PG8_BAR; PG8_SCHED;
;             PG8_LDA(At, 0, 1); PG8_STAGE(PG8_SB(0, 0), b2, voffB); PG8_STAGE(PG8_SB(0, 1), b2 + hstep, voffB); PG8_STAGE(PG8_SA(0, 0), a2, voffA);
;             PG8_WAIT_V(8); PG8_WAIT_L(0); PG8_BAR; PG8_MMA(1, 0, At, B0); PG8_MMA(1, 1, At, B1); PG8_BAR; PG8_SCHED;
;             PG8_LDB(B0, 1, 0); PG8_LDB(B1, 1, 1); PG8_SCHED; PG8_LDA(At, 1, 0); PG8_STAGE(PG8_SA(0, 1), a2 + hstepA, voffA);
;             PG8_WAIT_V(8); PG8_WAIT_L(0); PG8_BAR; PG8_MMA(0, 0, At, B0); PG8_MMA(0, 1, At, B1); PG8_BAR; PG8_SCHED;
	s_setprio 1
	s_waitcnt lgkmcnt(0)
	v_mfma_f32_16x16x32_bf16 v[68:71], v[72:75], v[168:171], v[68:71]
	v_mfma_f32_16x16x32_bf16 v[68:71], v[76:79], v[172:175], v[68:71]
	v_mfma_f32_16x16x32_bf16 v[64:67], v[88:91], v[172:175], v[64:67]
	v_mfma_f32_16x16x32_bf16 v[64:67], v[80:83], v[168:171], v[64:67]
	v_mfma_f32_16x16x32_bf16 v[48:51], v[80:83], v[176:179], v[48:51]
	v_mfma_f32_16x16x32_bf16 v[48:51], v[88:91], v[186:189], v[48:51]
	v_mfma_f32_16x16x32_bf16 v[52:55], v[76:79], v[186:189], v[52:55]
	v_mfma_f32_16x16x32_bf16 v[52:55], v[72:75], v[176:179], v[52:55]
	v_mfma_f32_16x16x32_bf16 v[34:37], v[72:75], v[200:203], v[36:39]
	v_mfma_f32_16x16x32_bf16 v[34:37], v[76:79], v[204:207], v[34:37]
	v_mfma_f32_16x16x32_bf16 v[26:29], v[88:91], v[204:207], v[26:29]
	v_mfma_f32_16x16x32_bf16 v[26:29], v[80:83], v[200:203], v[26:29]
	v_mfma_f32_16x16x32_bf16 v[10:13], v[80:83], v[208:211], v[10:13]
	v_mfma_f32_16x16x32_bf16 v[10:13], v[88:91], v[212:215], v[10:13]
	v_mfma_f32_16x16x32_bf16 v[14:17], v[76:79], v[212:215], v[14:17]
	v_mfma_f32_16x16x32_bf16 v[14:17], v[72:75], v[208:211], v[14:17]
	v_mfma_f32_16x16x32_bf16 v[6:9], v[152:155], v[208:211], v[6:9]
	v_mfma_f32_16x16x32_bf16 v[6:9], v[156:159], v[212:215], v[6:9]
	v_mfma_f32_16x16x32_bf16 v[2:5], v[164:167], v[212:215], v[2:5]
	v_mfma_f32_16x16x32_bf16 v[2:5], v[160:163], v[208:211], v[2:5]
	v_mfma_f32_16x16x32_bf16 v[18:21], v[160:163], v[200:203], v[18:21]
	v_mfma_f32_16x16x32_bf16 v[18:21], v[164:167], v[204:207], v[18:21]
	v_mfma_f32_16x16x32_bf16 v[22:25], v[156:159], v[204:207], v[22:25]
	v_mfma_f32_16x16x32_bf16 v[22:25], v[152:155], v[200:203], v[22:25]
	v_mfma_f32_16x16x32_bf16 v[44:47], v[152:155], v[176:179], v[44:47]
	v_mfma_f32_16x16x32_bf16 v[44:47], v[156:159], v[186:189], v[44:47]
	v_mfma_f32_16x16x32_bf16 v[40:43], v[164:167], v[186:189], v[40:43]
	v_mfma_f32_16x16x32_bf16 v[40:43], v[160:163], v[176:179], v[40:43]
	v_mfma_f32_16x16x32_bf16 v[56:59], v[160:163], v[168:171], v[56:59]
	v_mfma_f32_16x16x32_bf16 v[56:59], v[164:167], v[172:175], v[56:59]
	v_mfma_f32_16x16x32_bf16 v[60:63], v[156:159], v[172:175], v[60:63]
	v_mfma_f32_16x16x32_bf16 v[60:63], v[152:155], v[168:171], v[60:63]
	s_setprio 0
	s_barrier
	s_add_i32 s27, 0, 0x18000
	v_add_u32_e32 v32, s27, v239
	s_add_i32 s33, 0, 0x1c000
	ds_read_b128 v[72:75], v32
	ds_read_b128 v[76:79], v32 offset:1024
	ds_read_b128 v[80:83], v32 offset:2048
	ds_read_b128 v[88:91], v32 offset:3072
	v_add_u32_e32 v32, s33, v239
	ds_read_b128 v[152:155], v32
	ds_read_b128 v[156:159], v32 offset:1024
	ds_read_b128 v[160:163], v32 offset:2048
	ds_read_b128 v[164:167], v32 offset:3072
	s_add_u32 s28, s92, 0x200000
	s_addc_u32 s29, s93, 0
	s_mov_b32 m0, s42
	ds_read_b128 v[168:171], v251 offset:32768
	ds_read_b128 v[172:175], v251 offset:33792
	ds_read_b128 v[176:179], v251 offset:34816
	ds_read_b128 v[186:189], v251 offset:35840
	ds_read_b128 v[200:203], v251 offset:36864
	ds_read_b128 v[204:207], v251 offset:37888
	ds_read_b128 v[208:211], v251 offset:38912
	ds_read_b128 v[212:215], v251 offset:39936
	global_load_lds_dwordx4 v30, s[28:29]
	s_mov_b32 m0, s41
	s_nop 0
	global_load_lds_dwordx4 v180, s[28:29]
	s_waitcnt vmcnt(8)
	s_waitcnt lgkmcnt(0)
	s_barrier
	s_setprio 1
	s_waitcnt lgkmcnt(0)
	v_mfma_f32_16x16x32_bf16 v[84:87], v[72:75], v[168:171], v[84:87]
	v_mfma_f32_16x16x32_bf16 v[84:87], v[76:79], v[172:175], v[84:87]
	v_mfma_f32_16x16x32_bf16 v[148:151], v[88:91], v[172:175], v[148:151]
	v_mfma_f32_16x16x32_bf16 v[148:151], v[80:83], v[168:171], v[148:151]
	v_mfma_f32_16x16x32_bf16 v[132:135], v[80:83], v[176:179], v[132:135]
	v_mfma_f32_16x16x32_bf16 v[132:135], v[88:91], v[186:189], v[132:135]
	v_mfma_f32_16x16x32_bf16 v[136:139], v[76:79], v[186:189], v[136:139]
	v_mfma_f32_16x16x32_bf16 v[136:139], v[72:75], v[176:179], v[136:139]
	v_mfma_f32_16x16x32_bf16 v[120:123], v[72:75], v[200:203], v[120:123]
	v_mfma_f32_16x16x32_bf16 v[120:123], v[76:79], v[204:207], v[120:123]
	v_mfma_f32_16x16x32_bf16 v[116:119], v[88:91], v[204:207], v[116:119]
	v_mfma_f32_16x16x32_bf16 v[116:119], v[80:83], v[200:203], v[116:119]
	v_mfma_f32_16x16x32_bf16 v[100:103], v[80:83], v[208:211], v[100:103]
	v_mfma_f32_16x16x32_bf16 v[100:103], v[88:91], v[212:215], v[100:103]
	v_mfma_f32_16x16x32_bf16 v[104:107], v[76:79], v[212:215], v[104:107]
	v_mfma_f32_16x16x32_bf16 v[104:107], v[72:75], v[208:211], v[104:107]
	v_mfma_f32_16x16x32_bf16 v[96:99], v[152:155], v[208:211], v[96:99]
	v_mfma_f32_16x16x32_bf16 v[96:99], v[156:159], v[212:215], v[96:99]
	v_mfma_f32_16x16x32_bf16 v[92:95], v[164:167], v[212:215], v[92:95]
	v_mfma_f32_16x16x32_bf16 v[92:95], v[160:163], v[208:211], v[92:95]
	v_mfma_f32_16x16x32_bf16 v[108:111], v[160:163], v[200:203], v[108:111]
	v_mfma_f32_16x16x32_bf16 v[108:111], v[164:167], v[204:207], v[108:111]
	v_mfma_f32_16x16x32_bf16 v[112:115], v[156:159], v[204:207], v[112:115]
	v_mfma_f32_16x16x32_bf16 v[112:115], v[152:155], v[200:203], v[112:115]
	v_mfma_f32_16x16x32_bf16 v[128:131], v[152:155], v[176:179], v[128:131]
	v_mfma_f32_16x16x32_bf16 v[128:131], v[156:159], v[186:189], v[128:131]
	v_mfma_f32_16x16x32_bf16 v[124:127], v[164:167], v[186:189], v[124:127]
	v_mfma_f32_16x16x32_bf16 v[124:127], v[160:163], v[176:179], v[124:127]
	v_mfma_f32_16x16x32_bf16 v[140:143], v[160:163], v[168:171], v[140:143]
	v_mfma_f32_16x16x32_bf16 v[140:143], v[164:167], v[172:175], v[140:143]
	v_mfma_f32_16x16x32_bf16 v[144:147], v[156:159], v[172:175], v[144:147]
	v_mfma_f32_16x16x32_bf16 v[144:147], v[152:155], v[168:171], v[144:147]
	s_setprio 0
	s_barrier
; #define PG8_STAGE(bufoff, gbase, voff) do { _Pragma("unroll") for (int _i = 0; _i < 2; ++_i) \
;         __builtin_amdgcn_global_load_lds((const unsigned*)((const char*)(gbase) + (voff)[_i]), (PG8_LAS unsigned*)(lds + (bufoff) + ldsw + _i * 8192), 16, 0, 0); } while (0)
; #define PG8_LDA(dst, b, h) do { _Pragma("unroll") for (int m = 0; m < 4; ++m) _Pragma("unroll") for (int k = 0; k < 2; ++k) dst[m][k] = *(const PG8_LAS bf16x8*)(lds + PG8_SA(b, h) + aoff + m * 2048 + k * 1024); } while (0)
; #define PG8_MMA(ai, bj, At, Bt) do { __builtin_amdgcn_s_setprio(1); _Pragma("unroll") for (int m = 0; m < 4; ++m) _Pragma("unroll") for (int n = 0; n < 2; ++n) _Pragma("unroll") for (int k = 0; k < 2; ++k) \
;         acc[ai][bj][m][n] = __builtin_amdgcn_mfma_f32_16x16x32_bf16(Bt[n][k], At[m][k], acc[ai][bj][m][n], 0, 0, 0); __builtin_amdgcn_s_setprio(0); } while (0)
; #define PG8_WAIT_V(n) asm volatile("s_waitcnt vmcnt(" #n ")" ::: "memory")
; #define PG8_WAIT_L(n) asm volatile("s_waitcnt lgkmcnt(" #n ")" ::: "memory")
; #define PG8_BAR __builtin_amdgcn_s_barrier()
; #define PG8_SCHED __builtin_amdgcn_sched_barrier(0)
;     ...
;         for (int t = 0; t < nt; t += 2) {
;     ...
;             PG8_LDA(At, 1, 1); PG8_STAGE(PG8_SB(1, 0), b3, voffB); PG8_STAGE(PG8_SB(1, 1), b3 + hstep, voffB); PG8_STAGE(PG8_SA(1, 0), a3, voffA);
;             PG8_WAIT_V(8); PG8_WAIT_L(0); PG8_BAR; PG8_MMA(1, 0, At, B0); PG8_MMA(1, 1, At, B1); PG8_BAR; PG8_SCHED;
	s_add_i32 s27, s27, s3
	v_lshl_add_u64 v[38:39], v[190:191], 0, s[64:65]
	s_mov_b32 m0, s27
	ds_read_b128 v[168:171], v251 offset:49152
	ds_read_b128 v[172:175], v251 offset:50176
	ds_read_b128 v[176:179], v251 offset:51200
	ds_read_b128 v[186:189], v251 offset:52224
	ds_read_b128 v[200:203], v251 offset:53248
	ds_read_b128 v[204:207], v251 offset:54272
	ds_read_b128 v[208:211], v251 offset:55296
	ds_read_b128 v[212:215], v251 offset:56320
	global_load_lds_dwordx4 v[38:39], off
	s_add_i32 m0, s27, 0x2000
	s_add_u32 s28, s38, 0x200080
	v_lshl_add_u64 v[38:39], v[216:217], 0, s[64:65]
	s_addc_u32 s29, s39, 0
	s_add_i32 s27, s33, s3
	global_load_lds_dwordx4 v[38:39], off
	s_mov_b32 m0, s27
	s_nop 0
	global_load_lds_dwordx4 v30, s[28:29]
	s_add_i32 m0, s27, 0x2000
	s_nop 0
	global_load_lds_dwordx4 v180, s[28:29]
	v_lshl_add_u64 v[38:39], v[218:219], 0, s[64:65]
	s_mov_b32 m0, s53
	s_nop 0
	global_load_lds_dwordx4 v[38:39], off
	v_lshl_add_u64 v[38:39], v[220:221], 0, s[64:65]
	s_mov_b32 m0, s10
	s_nop 0
	global_load_lds_dwordx4 v[38:39], off
	s_waitcnt vmcnt(8)
	s_waitcnt lgkmcnt(0)
	s_barrier
	s_setprio 1
	s_waitcnt lgkmcnt(0)
	v_mfma_f32_16x16x32_bf16 v[68:71], v[72:75], v[168:171], v[68:71]
	v_mfma_f32_16x16x32_bf16 v[68:71], v[76:79], v[172:175], v[68:71]
	v_mfma_f32_16x16x32_bf16 v[64:67], v[88:91], v[172:175], v[64:67]
	v_mfma_f32_16x16x32_bf16 v[64:67], v[80:83], v[168:171], v[64:67]
	v_mfma_f32_16x16x32_bf16 v[48:51], v[80:83], v[176:179], v[48:51]
	v_mfma_f32_16x16x32_bf16 v[48:51], v[88:91], v[186:189], v[48:51]
	v_mfma_f32_16x16x32_bf16 v[52:55], v[76:79], v[186:189], v[52:55]
	v_mfma_f32_16x16x32_bf16 v[52:55], v[72:75], v[176:179], v[52:55]
	v_mfma_f32_16x16x32_bf16 v[34:37], v[72:75], v[200:203], v[34:37]
	v_mfma_f32_16x16x32_bf16 v[36:39], v[76:79], v[204:207], v[34:37]
	v_mfma_f32_16x16x32_bf16 v[26:29], v[88:91], v[204:207], v[26:29]
	v_mfma_f32_16x16x32_bf16 v[26:29], v[80:83], v[200:203], v[26:29]
	v_mfma_f32_16x16x32_bf16 v[10:13], v[80:83], v[208:211], v[10:13]
	v_mfma_f32_16x16x32_bf16 v[10:13], v[88:91], v[212:215], v[10:13]
	v_mfma_f32_16x16x32_bf16 v[14:17], v[76:79], v[212:215], v[14:17]
	v_mfma_f32_16x16x32_bf16 v[14:17], v[72:75], v[208:211], v[14:17]
	v_mfma_f32_16x16x32_bf16 v[6:9], v[152:155], v[208:211], v[6:9]
	v_mfma_f32_16x16x32_bf16 v[6:9], v[156:159], v[212:215], v[6:9]
	v_mfma_f32_16x16x32_bf16 v[2:5], v[164:167], v[212:215], v[2:5]
	v_mfma_f32_16x16x32_bf16 v[2:5], v[160:163], v[208:211], v[2:5]
	v_mfma_f32_16x16x32_bf16 v[18:21], v[160:163], v[200:203], v[18:21]
	v_mfma_f32_16x16x32_bf16 v[18:21], v[164:167], v[204:207], v[18:21]
	v_mfma_f32_16x16x32_bf16 v[22:25], v[156:159], v[204:207], v[22:25]
	v_mfma_f32_16x16x32_bf16 v[22:25], v[152:155], v[200:203], v[22:25]
	v_mfma_f32_16x16x32_bf16 v[44:47], v[152:155], v[176:179], v[44:47]
	v_mfma_f32_16x16x32_bf16 v[44:47], v[156:159], v[186:189], v[44:47]
	v_mfma_f32_16x16x32_bf16 v[40:43], v[164:167], v[186:189], v[40:43]
	v_mfma_f32_16x16x32_bf16 v[40:43], v[160:163], v[176:179], v[40:43]
	v_mfma_f32_16x16x32_bf16 v[56:59], v[160:163], v[168:171], v[56:59]
	v_mfma_f32_16x16x32_bf16 v[56:59], v[164:167], v[172:175], v[56:59]
	v_mfma_f32_16x16x32_bf16 v[60:63], v[156:159], v[172:175], v[60:63]
	v_mfma_f32_16x16x32_bf16 v[60:63], v[152:155], v[168:171], v[60:63]
	s_setprio 0
	s_barrier
	s_add_i32 s27, s25, 2
	s_add_u32 s9, s9, 0x100
	s_addc_u32 s23, s23, 0
	s_cmp_ge_i32 s25, s40
	s_mov_b64 s[28:29], s[30:31]
	s_mov_b32 s25, s27
	s_cbranch_scc0 .LBB0_1454
	s_and_b64 vcc, exec, s[16:17]
	s_cbranch_vccz .LBB0_1457
	s_barrier
